# v54 plus 100 integer bit-trick bf16 RNE pair packs in NA/DSW attention replaced by v_cvt_pk_bf16_f32 (same RNE, fewer VALU)
# speedup vs baseline: 1.0085x; 1.0029x over previous
; #define LAS __attribute__((address_space(3)))
; __device__ __forceinline__ unsigned pk2(float lo, float hi) { return f2bf(lo) | (f2bf(hi) << 16); }
; template <int L>
; __device__ __forceinline__ void layer_body(const Args& args, LAS unsigned char* lds, const int wave, const int G, const int gw, const int NGW, const int lo, const int hi,
;                                            unsigned char* const ws_kernel, const XcdBarrier& bar, int& pid) {
;     ...
;                     for (int s = 0; s < 8; ++s) { const f32x4 p0 = sc[2 * s], p1 = sc[2 * s + 1]; v4u w; w.x = pk2(p0[0], p0[1]); w.y = pk2(p0[2], p0[3]); w.z = pk2(p1[0], p1[1]); w.w = pk2(p1[2], p1[3]); pbf[s] = __builtin_bit_cast(bf16x8, w); }
;                     __syncthreads();
; #pragma unroll
;                     for (int i = 0; i < 14; ++i) { const int kid = skey + 32 * i; *(LAS v4u*)(size_t)(IMG + vimg_off(kid, sch)) = rst[i]; }
;                     __syncthreads();
;                     if (unit + GH < UEND) { NA_LOADROWS(unit + GH, rst, D); NA_LOADQ(unit + GH); }
;                     f32x4 acc[8];
; #pragma unroll
;                     for (int mt = 0; mt < 8; ++mt) acc[mt] = (f32x4){0.f, 0.f, 0.f, 0.f};
;                     const int trq = (lane & 15) >> 2, trp = lane & 3;
; #pragma unroll
;                     for (int s = 0; s < 8; ++s) {
;                         const int ir0 = (r0w - krlo + s) * 40 + coloff;
; #pragma unroll
;                         for (int mh = 0; mh < 2; ++mh) {
;                             s16x4 lo[4], hi[4];
; #pragma unroll
;                             for (int m4 = 0; m4 < 4; ++m4) { const int mt = mh * 4 + m4, r0_ = ir0 + 4 * kg + trq, r1_ = ir0 + 16 + 4 * kg + trq, ch_ = 2 * mt + (trp >> 1);
;                                 lo[m4] = tr_read_b64(IMG + vimg_off(r0_, ch_) + 8u * (trp & 1)); hi[m4] = tr_read_b64(IMG + vimg_off(r1_, ch_) + 8u * (trp & 1)); }
;                             asm volatile("s_waitcnt lgkmcnt(0)" ::: "memory"); __builtin_amdgcn_sched_barrier(0);
; #pragma unroll
;                             for (int m4 = 0; m4 < 4; ++m4) { const int mt = mh * 4 + m4; const bf16x8 va = (bf16x8){lo[m4][0], lo[m4][1], lo[m4][2], lo[m4][3], hi[m4][0], hi[m4][1], hi[m4][2], hi[m4][3]};
;                                 acc[mt] = __builtin_amdgcn_mfma_f32_16x16x32_bf16(va, pbf[s], acc[mt], 0, 0, 0); }
.LBB0_843:
	v_cvt_pk_bf16_f32 v101, v196, v202
	v_cvt_pk_bf16_f32 v100, v192, v200
	v_cvt_pk_bf16_f32 v103, v201, v204
	v_cvt_pk_bf16_f32 v102, v198, v203
	v_cvt_pk_bf16_f32 v97, v186, v195
	v_cvt_pk_bf16_f32 v96, v182, v193
	v_cvt_pk_bf16_f32 v99, v194, v199
	v_cvt_pk_bf16_f32 v98, v189, v197
	v_cvt_pk_bf16_f32 v93, v180, v185
	v_cvt_pk_bf16_f32 v92, v179, v183
	v_cvt_pk_bf16_f32 v95, v184, v190
	v_cvt_pk_bf16_f32 v94, v181, v187
	v_cvt_pk_bf16_f32 v89, v142, v148
	v_cvt_pk_bf16_f32 v88, v138, v146
	v_cvt_pk_bf16_f32 v91, v147, v152
	v_cvt_pk_bf16_f32 v90, v144, v150
	v_cvt_pk_bf16_f32 v85, v134, v141
	v_cvt_pk_bf16_f32 v84, v130, v139
	v_cvt_pk_bf16_f32 v87, v140, v145
	v_cvt_pk_bf16_f32 v86, v136, v143
	v_cvt_pk_bf16_f32 v81, v126, v133
	v_cvt_pk_bf16_f32 v80, v122, v131
	v_bfe_u32 v78, v125, 16, 1
	v_add3_u32 v113, v125, v78, s23
	v_bfe_u32 v79, v118, 16, 1
	v_cvt_pk_bf16_f32 v83, v132, v137
	v_add3_u32 v79, v118, v79, s23
	v_cvt_pk_bf16_f32 v82, v128, v135
	v_lshrrev_b32_e32 v118, 16, v79
	v_cvt_pk_bf16_f32 v79, v124, v129
	v_cvt_pk_bf16_f32 v76, v75, v123
	v_cvt_pk_bf16_f32 v78, v120, v127
	v_and_or_b32 v77, v113, s89, v118
	v_bfe_u32 v114, v115, 16, 1
	v_add3_u32 v114, v115, v114, s23
	v_bfe_u32 v115, v72, 16, 1
	v_add3_u32 v72, v72, v115, s23
	v_lshrrev_b32_e32 v112, 2, v112
	v_lshrrev_b32_e32 v72, 16, v72
	v_cvt_pk_bf16_f32 v75, v116, v121
	v_or_b32_e32 v115, v110, v112
	s_add_i32 s6, s6, s15
	v_cvt_pk_bf16_f32 v73, v73, v117
	v_and_or_b32 v72, v114, s89, v72
	v_or_b32_e32 v113, 16, v115
	v_bfe_u32 v112, v111, 1, 1
	v_lshlrev_b32_e32 v111, 3, v111
	v_add_u32_e32 v114, s6, v115
	v_and_or_b32 v111, v111, 8, 0
	v_add_u32_e32 v116, s6, v113
	v_lshlrev_b32_e32 v117, 2, v114
	v_and_b32_e32 v152, 12, v117
	v_bfe_u32 v153, v114, 2, 2
	v_lshl_add_u32 v154, v114, 8, v111
	v_lshlrev_b32_e32 v114, 2, v116
	v_and_b32_e32 v155, 12, v114
	v_bitop3_b32 v114, v152, v112, v153 bitop3:0x36
	v_bfe_u32 v156, v116, 2, 2
	v_lshl_add_u32 v114, v114, 4, v154
	v_lshl_add_u32 v157, v116, 8, v111
	ds_read_b64_tr_b16 v[120:121], v114
	v_bitop3_b32 v114, v155, v112, v156 bitop3:0x36
	v_lshl_add_u32 v114, v114, 4, v157
	ds_read_b64_tr_b16 v[122:123], v114
	v_or_b32_e32 v114, 2, v112
	v_bitop3_b32 v116, v152, v114, v153 bitop3:0x36
	v_lshl_add_u32 v116, v116, 4, v154
	ds_read_b64_tr_b16 v[124:125], v116
	v_bitop3_b32 v116, v155, v114, v156 bitop3:0x36
	v_lshl_add_u32 v116, v116, 4, v157
	ds_read_b64_tr_b16 v[126:127], v116
	v_or_b32_e32 v116, 4, v112
	v_bitop3_b32 v117, v152, v116, v153 bitop3:0x36
	v_lshl_add_u32 v117, v117, 4, v154
	ds_read_b64_tr_b16 v[128:129], v117
	v_bitop3_b32 v117, v155, v116, v156 bitop3:0x36
	v_lshl_add_u32 v117, v117, 4, v157
	ds_read_b64_tr_b16 v[130:131], v117
	v_or_b32_e32 v117, 6, v112
	v_bitop3_b32 v118, v152, v117, v153 bitop3:0x36
	v_lshl_add_u32 v118, v118, 4, v154
	ds_read_b64_tr_b16 v[132:133], v118
	v_bitop3_b32 v118, v155, v117, v156 bitop3:0x36
	v_lshl_add_u32 v118, v118, 4, v157
	ds_read_b64_tr_b16 v[134:135], v118
	s_waitcnt lgkmcnt(0)
	v_cvt_pk_bf16_f32 v74, v74, v119
	v_add_f32_e32 v104, v149, v151
	v_or_b32_e32 v118, 8, v112
	v_bitop3_b32 v119, v152, v118, v153 bitop3:0x36
	v_lshl_add_u32 v119, v119, 4, v154
	v_mfma_f32_16x16x32_bf16 v[136:139], v[120:123], v[100:103], 0
	ds_read_b64_tr_b16 v[122:123], v119
	v_bitop3_b32 v119, v155, v118, v156 bitop3:0x36
	v_lshl_add_u32 v119, v119, 4, v157
	v_mfma_f32_16x16x32_bf16 v[140:143], v[124:127], v[100:103], 0
	ds_read_b64_tr_b16 v[124:125], v119
	v_or_b32_e32 v119, 10, v112
	v_bitop3_b32 v120, v152, v119, v153 bitop3:0x36
	v_lshl_add_u32 v120, v120, 4, v154
	v_mfma_f32_16x16x32_bf16 v[126:129], v[128:131], v[100:103], 0
	ds_read_b64_tr_b16 v[130:131], v120
	v_bitop3_b32 v120, v155, v119, v156 bitop3:0x36
	v_lshl_add_u32 v120, v120, 4, v157
	v_mfma_f32_16x16x32_bf16 v[144:147], v[132:135], v[100:103], 0
	ds_read_b64_tr_b16 v[132:133], v120
	v_or_b32_e32 v120, 12, v112
	v_bitop3_b32 v121, v152, v120, v153 bitop3:0x36
	v_lshl_add_u32 v121, v121, 4, v154
	ds_read_b64_tr_b16 v[148:149], v121
	v_bitop3_b32 v121, v155, v120, v156 bitop3:0x36
	v_lshl_add_u32 v121, v121, 4, v157
	ds_read_b64_tr_b16 v[150:151], v121
	v_or_b32_e32 v121, 14, v112
	v_bitop3_b32 v134, v152, v121, v153 bitop3:0x36
	v_lshl_add_u32 v134, v134, 4, v154
	ds_read_b64_tr_b16 v[152:153], v134
	v_bitop3_b32 v134, v155, v121, v156 bitop3:0x36
	v_lshl_add_u32 v134, v134, 4, v157
	ds_read_b64_tr_b16 v[154:155], v134
	s_waitcnt lgkmcnt(0)
	s_add_i32 s7, s7, s15
	v_add_u32_e32 v134, s7, v115
	v_add_u32_e32 v135, s7, v113
	v_lshlrev_b32_e32 v156, 2, v134
	v_and_b32_e32 v168, 12, v156
	v_bfe_u32 v169, v134, 2, 2
	v_lshl_add_u32 v170, v134, 8, v111
	v_lshlrev_b32_e32 v134, 2, v135
	v_and_b32_e32 v171, 12, v134
	v_bitop3_b32 v134, v168, v112, v169 bitop3:0x36
	v_bfe_u32 v172, v135, 2, 2
	v_lshl_add_u32 v134, v134, 4, v170
	v_mfma_f32_16x16x32_bf16 v[122:125], v[122:125], v[100:103], 0
	v_lshl_add_u32 v173, v135, 8, v111
	v_mfma_f32_16x16x32_bf16 v[130:133], v[130:133], v[100:103], 0
	v_mfma_f32_16x16x32_bf16 v[148:151], v[148:151], v[100:103], 0
	v_mfma_f32_16x16x32_bf16 v[100:103], v[152:155], v[100:103], 0
	ds_read_b64_tr_b16 v[152:153], v134
	v_bitop3_b32 v134, v171, v112, v172 bitop3:0x36
	v_lshl_add_u32 v134, v134, 4, v173
	ds_read_b64_tr_b16 v[154:155], v134
	v_bitop3_b32 v134, v168, v114, v169 bitop3:0x36
	v_lshl_add_u32 v134, v134, 4, v170
	ds_read_b64_tr_b16 v[156:157], v134
	v_bitop3_b32 v134, v171, v114, v172 bitop3:0x36
	v_lshl_add_u32 v134, v134, 4, v173
	ds_read_b64_tr_b16 v[158:159], v134
	v_bitop3_b32 v134, v168, v116, v169 bitop3:0x36
	v_lshl_add_u32 v134, v134, 4, v170
	ds_read_b64_tr_b16 v[160:161], v134
	v_bitop3_b32 v134, v171, v116, v172 bitop3:0x36
	v_lshl_add_u32 v134, v134, 4, v173
	ds_read_b64_tr_b16 v[162:163], v134
	v_bitop3_b32 v134, v168, v117, v169 bitop3:0x36
	v_lshl_add_u32 v134, v134, 4, v170
	ds_read_b64_tr_b16 v[164:165], v134
	v_bitop3_b32 v134, v171, v117, v172 bitop3:0x36
	v_lshl_add_u32 v134, v134, 4, v173
	ds_read_b64_tr_b16 v[166:167], v134
	s_waitcnt lgkmcnt(0)
; __device__ __forceinline__ s16x4 tr_read_b64(unsigned addr) { s16x4 r; asm volatile("ds_read_b64_tr_b16 %0, %1" : "=v"(r) : "v"(addr) : "memory"); return r; }
; template <int L>
; __device__ __forceinline__ void layer_body(const Args& args, LAS unsigned char* lds, const int wave, const int G, const int gw, const int NGW, const int lo, const int hi,
;                                            unsigned char* const ws_kernel, const XcdBarrier& bar, int& pid) {
;     ...
;                     for (int s = 0; s < 8; ++s) {
;                         const int ir0 = (r0w - krlo + s) * 40 + coloff;
; #pragma unroll
;                         for (int mh = 0; mh < 2; ++mh) {
;                             s16x4 lo[4], hi[4];
; #pragma unroll
;                             for (int m4 = 0; m4 < 4; ++m4) { const int mt = mh * 4 + m4, r0_ = ir0 + 4 * kg + trq, r1_ = ir0 + 16 + 4 * kg + trq, ch_ = 2 * mt + (trp >> 1);
;                                 lo[m4] = tr_read_b64(IMG + vimg_off(r0_, ch_) + 8u * (trp & 1)); hi[m4] = tr_read_b64(IMG + vimg_off(r1_, ch_) + 8u * (trp & 1)); }
;                             asm volatile("s_waitcnt lgkmcnt(0)" ::: "memory"); __builtin_amdgcn_sched_barrier(0);
; #pragma unroll
;                             for (int m4 = 0; m4 < 4; ++m4) { const int mt = mh * 4 + m4; const bf16x8 va = (bf16x8){lo[m4][0], lo[m4][1], lo[m4][2], lo[m4][3], hi[m4][0], hi[m4][1], hi[m4][2], hi[m4][3]};
;                                 acc[mt] = __builtin_amdgcn_mfma_f32_16x16x32_bf16(va, pbf[s], acc[mt], 0, 0, 0); }
	v_mfma_f32_16x16x32_bf16 v[134:137], v[152:155], v[96:99], v[136:139]
	v_mfma_f32_16x16x32_bf16 v[138:141], v[156:159], v[96:99], v[140:143]
	v_mfma_f32_16x16x32_bf16 v[142:145], v[164:167], v[96:99], v[144:147]
	s_nop 2
	v_bitop3_b32 v146, v168, v118, v169 bitop3:0x36
	v_lshl_add_u32 v146, v146, 4, v170
	ds_read_b64_tr_b16 v[152:153], v146
	v_bitop3_b32 v146, v171, v118, v172 bitop3:0x36
	v_lshl_add_u32 v146, v146, 4, v173
	ds_read_b64_tr_b16 v[154:155], v146
	v_bitop3_b32 v146, v168, v119, v169 bitop3:0x36
	v_lshl_add_u32 v146, v146, 4, v170
	ds_read_b64_tr_b16 v[156:157], v146
	v_bitop3_b32 v146, v171, v119, v172 bitop3:0x36
	v_lshl_add_u32 v146, v146, 4, v173
	ds_read_b64_tr_b16 v[158:159], v146
	v_bitop3_b32 v146, v168, v120, v169 bitop3:0x36
	v_lshl_add_u32 v146, v146, 4, v170
	v_mfma_f32_16x16x32_bf16 v[126:129], v[160:163], v[96:99], v[126:129]
	ds_read_b64_tr_b16 v[160:161], v146
	v_bitop3_b32 v146, v171, v120, v172 bitop3:0x36
	v_lshl_add_u32 v146, v146, 4, v173
	ds_read_b64_tr_b16 v[162:163], v146
	v_bitop3_b32 v146, v168, v121, v169 bitop3:0x36
	v_lshl_add_u32 v146, v146, 4, v170
	ds_read_b64_tr_b16 v[164:165], v146
	v_bitop3_b32 v146, v171, v121, v172 bitop3:0x36
	v_lshl_add_u32 v146, v146, 4, v173
	ds_read_b64_tr_b16 v[166:167], v146
	s_waitcnt lgkmcnt(0)
	s_add_i32 s8, s8, s15
	v_mfma_f32_16x16x32_bf16 v[122:125], v[152:155], v[96:99], v[122:125]
	v_mfma_f32_16x16x32_bf16 v[130:133], v[156:159], v[96:99], v[130:133]
	v_mfma_f32_16x16x32_bf16 v[146:149], v[160:163], v[96:99], v[148:151]
	v_mfma_f32_16x16x32_bf16 v[96:99], v[164:167], v[96:99], v[100:103]
	s_nop 2
	v_add_u32_e32 v100, s8, v115
	v_add_u32_e32 v101, s8, v113
	v_lshlrev_b32_e32 v102, 2, v100
	v_and_b32_e32 v162, 12, v102
	v_bfe_u32 v163, v100, 2, 2
	v_lshl_add_u32 v164, v100, 8, v111
	v_lshlrev_b32_e32 v100, 2, v101
	v_and_b32_e32 v165, 12, v100
	v_bfe_u32 v166, v101, 2, 2
	v_bitop3_b32 v100, v162, v112, v163 bitop3:0x36
	v_lshl_add_u32 v167, v101, 8, v111
	v_lshl_add_u32 v100, v100, 4, v164
	v_bitop3_b32 v102, v165, v112, v166 bitop3:0x36
	ds_read_b64_tr_b16 v[100:101], v100
	v_lshl_add_u32 v102, v102, 4, v167
	v_bitop3_b32 v150, v162, v114, v163 bitop3:0x36
	ds_read_b64_tr_b16 v[102:103], v102
	v_lshl_add_u32 v150, v150, 4, v164
	v_bitop3_b32 v152, v165, v114, v166 bitop3:0x36
	ds_read_b64_tr_b16 v[150:151], v150
	v_lshl_add_u32 v152, v152, 4, v167
	v_bitop3_b32 v154, v162, v116, v163 bitop3:0x36
	ds_read_b64_tr_b16 v[152:153], v152
	v_lshl_add_u32 v154, v154, 4, v164
	v_bitop3_b32 v156, v165, v116, v166 bitop3:0x36
	ds_read_b64_tr_b16 v[154:155], v154
	v_lshl_add_u32 v156, v156, 4, v167
	v_bitop3_b32 v158, v162, v117, v163 bitop3:0x36
	ds_read_b64_tr_b16 v[156:157], v156
	v_lshl_add_u32 v158, v158, 4, v164
	v_bitop3_b32 v160, v165, v117, v166 bitop3:0x36
	ds_read_b64_tr_b16 v[158:159], v158
	v_lshl_add_u32 v160, v160, 4, v167
	ds_read_b64_tr_b16 v[160:161], v160
	s_waitcnt lgkmcnt(0)
	v_mfma_f32_16x16x32_bf16 v[100:103], v[100:103], v[92:95], v[134:137]
	v_mfma_f32_16x16x32_bf16 v[134:137], v[150:153], v[92:95], v[138:141]
	v_bitop3_b32 v150, v162, v119, v163 bitop3:0x36
	v_lshl_add_u32 v150, v150, 4, v164
	v_bitop3_b32 v152, v165, v119, v166 bitop3:0x36
	v_mfma_f32_16x16x32_bf16 v[138:141], v[158:161], v[92:95], v[142:145]
	v_lshl_add_u32 v152, v152, 4, v167
	v_bitop3_b32 v158, v162, v121, v163 bitop3:0x36
	v_lshl_add_u32 v158, v158, 4, v164
	v_bitop3_b32 v142, v162, v118, v163 bitop3:0x36
	v_lshl_add_u32 v142, v142, 4, v164
	v_bitop3_b32 v144, v165, v118, v166 bitop3:0x36
	ds_read_b64_tr_b16 v[142:143], v142
	v_lshl_add_u32 v144, v144, 4, v167
	ds_read_b64_tr_b16 v[144:145], v144
	v_mfma_f32_16x16x32_bf16 v[126:129], v[154:157], v[92:95], v[126:129]
	ds_read_b64_tr_b16 v[150:151], v150
	v_bitop3_b32 v154, v162, v120, v163 bitop3:0x36
	ds_read_b64_tr_b16 v[152:153], v152
	v_lshl_add_u32 v154, v154, 4, v164
	v_bitop3_b32 v156, v165, v120, v166 bitop3:0x36
	ds_read_b64_tr_b16 v[154:155], v154
	v_lshl_add_u32 v156, v156, 4, v167
	ds_read_b64_tr_b16 v[156:157], v156
	v_bitop3_b32 v160, v165, v121, v166 bitop3:0x36
	ds_read_b64_tr_b16 v[158:159], v158
	v_lshl_add_u32 v160, v160, 4, v167
	ds_read_b64_tr_b16 v[160:161], v160
	s_waitcnt lgkmcnt(0)
	s_add_i32 s37, s37, s15
	v_mfma_f32_16x16x32_bf16 v[122:125], v[142:145], v[92:95], v[122:125]
	v_mfma_f32_16x16x32_bf16 v[130:133], v[150:153], v[92:95], v[130:133]
	v_mfma_f32_16x16x32_bf16 v[142:145], v[154:157], v[92:95], v[146:149]
	v_mfma_f32_16x16x32_bf16 v[92:95], v[158:161], v[92:95], v[96:99]
	s_nop 2
	v_add_u32_e32 v96, s37, v115
	v_add_u32_e32 v97, s37, v113
	v_lshlrev_b32_e32 v98, 2, v96
	v_and_b32_e32 v158, 12, v98
	v_bfe_u32 v159, v96, 2, 2
	v_lshl_add_u32 v160, v96, 8, v111
	v_lshlrev_b32_e32 v96, 2, v97
	v_and_b32_e32 v161, 12, v96
	v_bfe_u32 v162, v97, 2, 2
	v_bitop3_b32 v96, v158, v112, v159 bitop3:0x36
	v_lshl_add_u32 v163, v97, 8, v111
	v_lshl_add_u32 v96, v96, 4, v160
	v_bitop3_b32 v98, v161, v112, v162 bitop3:0x36
	ds_read_b64_tr_b16 v[96:97], v96
	v_lshl_add_u32 v98, v98, 4, v163
	v_bitop3_b32 v146, v158, v114, v159 bitop3:0x36
	ds_read_b64_tr_b16 v[98:99], v98
	v_lshl_add_u32 v146, v146, 4, v160
	v_bitop3_b32 v148, v161, v114, v162 bitop3:0x36
	ds_read_b64_tr_b16 v[146:147], v146
	v_lshl_add_u32 v148, v148, 4, v163
	v_bitop3_b32 v150, v158, v116, v159 bitop3:0x36
	ds_read_b64_tr_b16 v[148:149], v148
	v_lshl_add_u32 v150, v150, 4, v160
	v_bitop3_b32 v152, v161, v116, v162 bitop3:0x36
	ds_read_b64_tr_b16 v[150:151], v150
	v_lshl_add_u32 v152, v152, 4, v163
	v_bitop3_b32 v154, v158, v117, v159 bitop3:0x36
	ds_read_b64_tr_b16 v[152:153], v152
	v_lshl_add_u32 v154, v154, 4, v160
	v_bitop3_b32 v156, v161, v117, v162 bitop3:0x36
	ds_read_b64_tr_b16 v[154:155], v154
	v_lshl_add_u32 v156, v156, 4, v163
	ds_read_b64_tr_b16 v[156:157], v156
	s_waitcnt lgkmcnt(0)
; __device__ __forceinline__ s16x4 tr_read_b64(unsigned addr) { s16x4 r; asm volatile("ds_read_b64_tr_b16 %0, %1" : "=v"(r) : "v"(addr) : "memory"); return r; }
; template <int L>
; __device__ __forceinline__ void layer_body(const Args& args, LAS unsigned char* lds, const int wave, const int G, const int gw, const int NGW, const int lo, const int hi,
;                                            unsigned char* const ws_kernel, const XcdBarrier& bar, int& pid) {
;     ...
;                     for (int s = 0; s < 8; ++s) {
;                         const int ir0 = (r0w - krlo + s) * 40 + coloff;
; #pragma unroll
;                         for (int mh = 0; mh < 2; ++mh) {
;                             s16x4 lo[4], hi[4];
; #pragma unroll
;                             for (int m4 = 0; m4 < 4; ++m4) { const int mt = mh * 4 + m4, r0_ = ir0 + 4 * kg + trq, r1_ = ir0 + 16 + 4 * kg + trq, ch_ = 2 * mt + (trp >> 1);
;                                 lo[m4] = tr_read_b64(IMG + vimg_off(r0_, ch_) + 8u * (trp & 1)); hi[m4] = tr_read_b64(IMG + vimg_off(r1_, ch_) + 8u * (trp & 1)); }
;                             asm volatile("s_waitcnt lgkmcnt(0)" ::: "memory"); __builtin_amdgcn_sched_barrier(0);
; #pragma unroll
;                             for (int m4 = 0; m4 < 4; ++m4) { const int mt = mh * 4 + m4; const bf16x8 va = (bf16x8){lo[m4][0], lo[m4][1], lo[m4][2], lo[m4][3], hi[m4][0], hi[m4][1], hi[m4][2], hi[m4][3]};
;                                 acc[mt] = __builtin_amdgcn_mfma_f32_16x16x32_bf16(va, pbf[s], acc[mt], 0, 0, 0); }
	v_mfma_f32_16x16x32_bf16 v[96:99], v[96:99], v[88:91], v[100:103]
	v_mfma_f32_16x16x32_bf16 v[100:103], v[146:149], v[88:91], v[134:137]
	v_bitop3_b32 v146, v158, v119, v159 bitop3:0x36
	v_lshl_add_u32 v146, v146, 4, v160
	v_bitop3_b32 v148, v161, v119, v162 bitop3:0x36
	v_mfma_f32_16x16x32_bf16 v[134:137], v[154:157], v[88:91], v[138:141]
	v_lshl_add_u32 v148, v148, 4, v163
	v_bitop3_b32 v154, v158, v121, v159 bitop3:0x36
	v_lshl_add_u32 v154, v154, 4, v160
	v_bitop3_b32 v138, v158, v118, v159 bitop3:0x36
	v_lshl_add_u32 v138, v138, 4, v160
	v_bitop3_b32 v140, v161, v118, v162 bitop3:0x36
	ds_read_b64_tr_b16 v[138:139], v138
	v_lshl_add_u32 v140, v140, 4, v163
	ds_read_b64_tr_b16 v[140:141], v140
	v_mfma_f32_16x16x32_bf16 v[126:129], v[150:153], v[88:91], v[126:129]
	ds_read_b64_tr_b16 v[146:147], v146
	v_bitop3_b32 v150, v158, v120, v159 bitop3:0x36
	ds_read_b64_tr_b16 v[148:149], v148
	v_lshl_add_u32 v150, v150, 4, v160
	v_bitop3_b32 v152, v161, v120, v162 bitop3:0x36
	ds_read_b64_tr_b16 v[150:151], v150
	v_lshl_add_u32 v152, v152, 4, v163
	ds_read_b64_tr_b16 v[152:153], v152
	v_bitop3_b32 v156, v161, v121, v162 bitop3:0x36
	ds_read_b64_tr_b16 v[154:155], v154
	v_lshl_add_u32 v156, v156, 4, v163
	ds_read_b64_tr_b16 v[156:157], v156
	s_waitcnt lgkmcnt(0)
	s_add_i32 s38, s38, s15
	v_mfma_f32_16x16x32_bf16 v[122:125], v[138:141], v[88:91], v[122:125]
	v_mfma_f32_16x16x32_bf16 v[130:133], v[146:149], v[88:91], v[130:133]
	v_mfma_f32_16x16x32_bf16 v[138:141], v[150:153], v[88:91], v[142:145]
	v_mfma_f32_16x16x32_bf16 v[88:91], v[154:157], v[88:91], v[92:95]
	s_nop 2
	v_add_u32_e32 v92, s38, v115
	v_add_u32_e32 v93, s38, v113
	v_lshlrev_b32_e32 v94, 2, v92
	v_and_b32_e32 v154, 12, v94
	v_bfe_u32 v155, v92, 2, 2
	v_lshl_add_u32 v156, v92, 8, v111
	v_lshlrev_b32_e32 v92, 2, v93
	v_and_b32_e32 v157, 12, v92
	v_bfe_u32 v158, v93, 2, 2
	v_bitop3_b32 v92, v154, v112, v155 bitop3:0x36
	v_lshl_add_u32 v159, v93, 8, v111
	v_lshl_add_u32 v92, v92, 4, v156
	v_bitop3_b32 v94, v157, v112, v158 bitop3:0x36
	ds_read_b64_tr_b16 v[92:93], v92
	v_lshl_add_u32 v94, v94, 4, v159
	v_bitop3_b32 v142, v154, v114, v155 bitop3:0x36
	ds_read_b64_tr_b16 v[94:95], v94
	v_lshl_add_u32 v142, v142, 4, v156
	v_bitop3_b32 v144, v157, v114, v158 bitop3:0x36
	ds_read_b64_tr_b16 v[142:143], v142
	v_lshl_add_u32 v144, v144, 4, v159
	v_bitop3_b32 v146, v154, v116, v155 bitop3:0x36
	ds_read_b64_tr_b16 v[144:145], v144
	v_lshl_add_u32 v146, v146, 4, v156
	v_bitop3_b32 v148, v157, v116, v158 bitop3:0x36
	ds_read_b64_tr_b16 v[146:147], v146
	v_lshl_add_u32 v148, v148, 4, v159
	v_bitop3_b32 v150, v154, v117, v155 bitop3:0x36
	ds_read_b64_tr_b16 v[148:149], v148
	v_lshl_add_u32 v150, v150, 4, v156
	v_bitop3_b32 v152, v157, v117, v158 bitop3:0x36
	ds_read_b64_tr_b16 v[150:151], v150
	v_lshl_add_u32 v152, v152, 4, v159
	ds_read_b64_tr_b16 v[152:153], v152
	s_waitcnt lgkmcnt(0)
	v_mfma_f32_16x16x32_bf16 v[92:95], v[92:95], v[84:87], v[96:99]
	v_mfma_f32_16x16x32_bf16 v[96:99], v[142:145], v[84:87], v[100:103]
	v_bitop3_b32 v142, v154, v119, v155 bitop3:0x36
	v_lshl_add_u32 v142, v142, 4, v156
	v_bitop3_b32 v144, v157, v119, v158 bitop3:0x36
	v_mfma_f32_16x16x32_bf16 v[100:103], v[146:149], v[84:87], v[126:129]
	v_lshl_add_u32 v144, v144, 4, v159
	v_bitop3_b32 v146, v154, v120, v155 bitop3:0x36
	v_lshl_add_u32 v146, v146, 4, v156
	v_mfma_f32_16x16x32_bf16 v[126:129], v[150:153], v[84:87], v[134:137]
	v_bitop3_b32 v148, v157, v120, v158 bitop3:0x36
	v_lshl_add_u32 v148, v148, 4, v159
	v_bitop3_b32 v150, v154, v121, v155 bitop3:0x36
	v_bitop3_b32 v134, v154, v118, v155 bitop3:0x36
	v_lshl_add_u32 v134, v134, 4, v156
	v_bitop3_b32 v136, v157, v118, v158 bitop3:0x36
	ds_read_b64_tr_b16 v[134:135], v134
	v_lshl_add_u32 v136, v136, 4, v159
	ds_read_b64_tr_b16 v[136:137], v136
	ds_read_b64_tr_b16 v[142:143], v142
	ds_read_b64_tr_b16 v[144:145], v144
	ds_read_b64_tr_b16 v[146:147], v146
	ds_read_b64_tr_b16 v[148:149], v148
	v_lshl_add_u32 v150, v150, 4, v156
	v_bitop3_b32 v152, v157, v121, v158 bitop3:0x36
	ds_read_b64_tr_b16 v[150:151], v150
	v_lshl_add_u32 v152, v152, 4, v159
	ds_read_b64_tr_b16 v[152:153], v152
	s_waitcnt lgkmcnt(0)
	s_add_i32 s39, s39, s15
	v_mfma_f32_16x16x32_bf16 v[122:125], v[134:137], v[84:87], v[122:125]
	v_mfma_f32_16x16x32_bf16 v[130:133], v[142:145], v[84:87], v[130:133]
	v_mfma_f32_16x16x32_bf16 v[134:137], v[146:149], v[84:87], v[138:141]
	v_mfma_f32_16x16x32_bf16 v[84:87], v[150:153], v[84:87], v[88:91]
	s_nop 2
	v_add_u32_e32 v88, s39, v115
	v_add_u32_e32 v89, s39, v113
	v_lshlrev_b32_e32 v90, 2, v88
	v_and_b32_e32 v150, 12, v90
	v_bfe_u32 v151, v88, 2, 2
	v_lshl_add_u32 v152, v88, 8, v111
	v_lshlrev_b32_e32 v88, 2, v89
	v_and_b32_e32 v153, 12, v88
	v_bfe_u32 v154, v89, 2, 2
	v_bitop3_b32 v88, v150, v112, v151 bitop3:0x36
	v_lshl_add_u32 v155, v89, 8, v111
	v_lshl_add_u32 v88, v88, 4, v152
	v_bitop3_b32 v90, v153, v112, v154 bitop3:0x36
	ds_read_b64_tr_b16 v[88:89], v88
	v_lshl_add_u32 v90, v90, 4, v155
	v_bitop3_b32 v138, v150, v114, v151 bitop3:0x36
	ds_read_b64_tr_b16 v[90:91], v90
	v_lshl_add_u32 v138, v138, 4, v152
	v_bitop3_b32 v140, v153, v114, v154 bitop3:0x36
	ds_read_b64_tr_b16 v[138:139], v138
	v_lshl_add_u32 v140, v140, 4, v155
	v_bitop3_b32 v142, v150, v116, v151 bitop3:0x36
	ds_read_b64_tr_b16 v[140:141], v140
	v_lshl_add_u32 v142, v142, 4, v152
	v_bitop3_b32 v144, v153, v116, v154 bitop3:0x36
	ds_read_b64_tr_b16 v[142:143], v142
	v_lshl_add_u32 v144, v144, 4, v155
	v_bitop3_b32 v146, v150, v117, v151 bitop3:0x36
	ds_read_b64_tr_b16 v[144:145], v144
	v_lshl_add_u32 v146, v146, 4, v152
	v_bitop3_b32 v148, v153, v117, v154 bitop3:0x36
	ds_read_b64_tr_b16 v[146:147], v146
	v_lshl_add_u32 v148, v148, 4, v155
	ds_read_b64_tr_b16 v[148:149], v148
	s_waitcnt lgkmcnt(0)
; __device__ __forceinline__ s16x4 tr_read_b64(unsigned addr) { s16x4 r; asm volatile("ds_read_b64_tr_b16 %0, %1" : "=v"(r) : "v"(addr) : "memory"); return r; }
; template <int L>
; __device__ __forceinline__ void layer_body(const Args& args, LAS unsigned char* lds, const int wave, const int G, const int gw, const int NGW, const int lo, const int hi,
;                                            unsigned char* const ws_kernel, const XcdBarrier& bar, int& pid) {
;     ...
;                     for (int s = 0; s < 8; ++s) {
;                         const int ir0 = (r0w - krlo + s) * 40 + coloff;
; #pragma unroll
;                         for (int mh = 0; mh < 2; ++mh) {
;                             s16x4 lo[4], hi[4];
; #pragma unroll
;                             for (int m4 = 0; m4 < 4; ++m4) { const int mt = mh * 4 + m4, r0_ = ir0 + 4 * kg + trq, r1_ = ir0 + 16 + 4 * kg + trq, ch_ = 2 * mt + (trp >> 1);
;                                 lo[m4] = tr_read_b64(IMG + vimg_off(r0_, ch_) + 8u * (trp & 1)); hi[m4] = tr_read_b64(IMG + vimg_off(r1_, ch_) + 8u * (trp & 1)); }
;                             asm volatile("s_waitcnt lgkmcnt(0)" ::: "memory"); __builtin_amdgcn_sched_barrier(0);
; #pragma unroll
;                             for (int m4 = 0; m4 < 4; ++m4) { const int mt = mh * 4 + m4; const bf16x8 va = (bf16x8){lo[m4][0], lo[m4][1], lo[m4][2], lo[m4][3], hi[m4][0], hi[m4][1], hi[m4][2], hi[m4][3]};
;                                 acc[mt] = __builtin_amdgcn_mfma_f32_16x16x32_bf16(va, pbf[s], acc[mt], 0, 0, 0); }
	v_bitop3_b32 v156, v150, v118, v151 bitop3:0x36
	v_mfma_f32_16x16x32_bf16 v[88:91], v[88:91], v[80:83], v[92:95]
	v_lshl_add_u32 v156, v156, 4, v152
	ds_read_b64_tr_b16 v[92:93], v156
	v_mfma_f32_16x16x32_bf16 v[96:99], v[138:141], v[80:83], v[96:99]
	s_nop 0
	v_bitop3_b32 v94, v153, v118, v154 bitop3:0x36
	v_lshl_add_u32 v94, v94, 4, v155
	v_bitop3_b32 v138, v150, v119, v151 bitop3:0x36
	ds_read_b64_tr_b16 v[94:95], v94
	v_lshl_add_u32 v138, v138, 4, v152
	v_bitop3_b32 v140, v153, v119, v154 bitop3:0x36
	v_mfma_f32_16x16x32_bf16 v[100:103], v[142:145], v[80:83], v[100:103]
	ds_read_b64_tr_b16 v[138:139], v138
	v_lshl_add_u32 v140, v140, 4, v155
	v_bitop3_b32 v142, v150, v120, v151 bitop3:0x36
	ds_read_b64_tr_b16 v[140:141], v140
	v_lshl_add_u32 v142, v142, 4, v152
	v_bitop3_b32 v144, v153, v120, v154 bitop3:0x36
	v_mfma_f32_16x16x32_bf16 v[126:129], v[146:149], v[80:83], v[126:129]
	ds_read_b64_tr_b16 v[142:143], v142
	v_lshl_add_u32 v144, v144, 4, v155
	v_bitop3_b32 v146, v150, v121, v151 bitop3:0x36
	ds_read_b64_tr_b16 v[144:145], v144
	v_lshl_add_u32 v146, v146, 4, v152
	v_bitop3_b32 v148, v153, v121, v154 bitop3:0x36
	ds_read_b64_tr_b16 v[146:147], v146
	v_lshl_add_u32 v148, v148, 4, v155
	ds_read_b64_tr_b16 v[148:149], v148
	s_waitcnt lgkmcnt(0)
	s_add_i32 s40, s40, s15
	v_mfma_f32_16x16x32_bf16 v[92:95], v[92:95], v[80:83], v[122:125]
	v_mfma_f32_16x16x32_bf16 v[122:125], v[138:141], v[80:83], v[130:133]
	v_mfma_f32_16x16x32_bf16 v[130:133], v[142:145], v[80:83], v[134:137]
	v_mfma_f32_16x16x32_bf16 v[80:83], v[146:149], v[80:83], v[84:87]
	s_nop 2
	v_add_u32_e32 v84, s40, v115
	v_add_u32_e32 v85, s40, v113
	v_lshlrev_b32_e32 v86, 2, v84
	v_and_b32_e32 v146, 12, v86
	v_bfe_u32 v147, v84, 2, 2
	v_lshl_add_u32 v148, v84, 8, v111
	v_lshlrev_b32_e32 v84, 2, v85
	v_and_b32_e32 v149, 12, v84
	v_bfe_u32 v150, v85, 2, 2
	v_bitop3_b32 v84, v146, v112, v147 bitop3:0x36
	v_lshl_add_u32 v151, v85, 8, v111
	v_lshl_add_u32 v84, v84, 4, v148
	v_bitop3_b32 v86, v149, v112, v150 bitop3:0x36
	ds_read_b64_tr_b16 v[84:85], v84
	v_lshl_add_u32 v86, v86, 4, v151
	v_bitop3_b32 v134, v146, v114, v147 bitop3:0x36
	ds_read_b64_tr_b16 v[86:87], v86
	v_lshl_add_u32 v134, v134, 4, v148
	v_bitop3_b32 v136, v149, v114, v150 bitop3:0x36
	ds_read_b64_tr_b16 v[134:135], v134
	v_lshl_add_u32 v136, v136, 4, v151
	v_bitop3_b32 v138, v146, v116, v147 bitop3:0x36
	ds_read_b64_tr_b16 v[136:137], v136
	v_lshl_add_u32 v138, v138, 4, v148
	v_bitop3_b32 v140, v149, v116, v150 bitop3:0x36
	ds_read_b64_tr_b16 v[138:139], v138
	v_lshl_add_u32 v140, v140, 4, v151
	v_bitop3_b32 v142, v146, v117, v147 bitop3:0x36
	ds_read_b64_tr_b16 v[140:141], v140
	v_lshl_add_u32 v142, v142, 4, v148
	v_bitop3_b32 v144, v149, v117, v150 bitop3:0x36
	ds_read_b64_tr_b16 v[142:143], v142
	v_lshl_add_u32 v144, v144, 4, v151
	ds_read_b64_tr_b16 v[144:145], v144
	s_waitcnt lgkmcnt(0)
	v_bitop3_b32 v152, v146, v118, v147 bitop3:0x36
	v_mfma_f32_16x16x32_bf16 v[84:87], v[84:87], v[76:79], v[88:91]
	v_lshl_add_u32 v152, v152, 4, v148
	ds_read_b64_tr_b16 v[88:89], v152
	v_mfma_f32_16x16x32_bf16 v[96:99], v[134:137], v[76:79], v[96:99]
	s_nop 0
	v_bitop3_b32 v90, v149, v118, v150 bitop3:0x36
	v_lshl_add_u32 v90, v90, 4, v151
	v_bitop3_b32 v134, v146, v119, v147 bitop3:0x36
	ds_read_b64_tr_b16 v[90:91], v90
	v_lshl_add_u32 v134, v134, 4, v148
	v_bitop3_b32 v136, v149, v119, v150 bitop3:0x36
	v_mfma_f32_16x16x32_bf16 v[100:103], v[138:141], v[76:79], v[100:103]
	ds_read_b64_tr_b16 v[134:135], v134
	v_lshl_add_u32 v136, v136, 4, v151
	v_bitop3_b32 v138, v146, v120, v147 bitop3:0x36
	ds_read_b64_tr_b16 v[136:137], v136
	v_lshl_add_u32 v138, v138, 4, v148
	v_bitop3_b32 v140, v149, v120, v150 bitop3:0x36
	v_mfma_f32_16x16x32_bf16 v[126:129], v[142:145], v[76:79], v[126:129]
	ds_read_b64_tr_b16 v[138:139], v138
	v_lshl_add_u32 v140, v140, 4, v151
	v_bitop3_b32 v142, v146, v121, v147 bitop3:0x36
	ds_read_b64_tr_b16 v[140:141], v140
	v_lshl_add_u32 v142, v142, 4, v148
	v_bitop3_b32 v144, v149, v121, v150 bitop3:0x36
	ds_read_b64_tr_b16 v[142:143], v142
	v_lshl_add_u32 v144, v144, 4, v151
	ds_read_b64_tr_b16 v[144:145], v144
	s_waitcnt lgkmcnt(0)
	s_add_i32 s41, s41, s15
	v_add_u32_e32 v115, s41, v115
	v_mfma_f32_16x16x32_bf16 v[88:91], v[88:91], v[76:79], v[92:95]
	v_add_u32_e32 v113, s41, v113
	v_bfe_u32 v147, v115, 2, 2
	v_lshl_add_u32 v148, v115, 8, v111
	v_lshlrev_b32_e32 v92, 2, v115
	v_and_b32_e32 v146, 12, v92
	v_lshlrev_b32_e32 v115, 2, v113
	v_mfma_f32_16x16x32_bf16 v[92:95], v[134:137], v[76:79], v[122:125]
	v_lshl_add_u32 v111, v113, 8, v111
	v_mfma_f32_16x16x32_bf16 v[122:125], v[138:141], v[76:79], v[130:133]
	v_and_b32_e32 v138, 12, v115
	v_bfe_u32 v139, v113, 2, 2
	v_mfma_f32_16x16x32_bf16 v[76:79], v[142:145], v[76:79], v[80:83]
	v_bitop3_b32 v130, v146, v116, v147 bitop3:0x36
	v_lshl_add_u32 v130, v130, 4, v148
	v_bitop3_b32 v116, v138, v116, v139 bitop3:0x36
	v_bitop3_b32 v80, v146, v112, v147 bitop3:0x36
	v_lshl_add_u32 v80, v80, 4, v148
	v_bitop3_b32 v82, v138, v112, v139 bitop3:0x36
	ds_read_b64_tr_b16 v[80:81], v80
	v_lshl_add_u32 v82, v82, 4, v111
	v_bitop3_b32 v112, v146, v114, v147 bitop3:0x36
	ds_read_b64_tr_b16 v[82:83], v82
	v_lshl_add_u32 v112, v112, 4, v148
	v_bitop3_b32 v114, v138, v114, v139 bitop3:0x36
	ds_read_b64_tr_b16 v[112:113], v112
	v_lshl_add_u32 v114, v114, 4, v111
	ds_read_b64_tr_b16 v[114:115], v114
	ds_read_b64_tr_b16 v[130:131], v130
	v_lshl_add_u32 v116, v116, 4, v111
	ds_read_b64_tr_b16 v[132:133], v116
	v_bitop3_b32 v116, v146, v117, v147 bitop3:0x36
	v_lshl_add_u32 v116, v116, 4, v148
	ds_read_b64_tr_b16 v[134:135], v116
	v_bitop3_b32 v116, v138, v117, v139 bitop3:0x36
	v_lshl_add_u32 v116, v116, 4, v111
	ds_read_b64_tr_b16 v[136:137], v116
	s_waitcnt lgkmcnt(0)
; __device__ __forceinline__ s16x4 tr_read_b64(unsigned addr) { s16x4 r; asm volatile("ds_read_b64_tr_b16 %0, %1" : "=v"(r) : "v"(addr) : "memory"); return r; }
; template <int L>
; __device__ __forceinline__ void layer_body(const Args& args, LAS unsigned char* lds, const int wave, const int G, const int gw, const int NGW, const int lo, const int hi,
;                                            unsigned char* const ws_kernel, const XcdBarrier& bar, int& pid) {
;     ...
;                     for (int s = 0; s < 8; ++s) {
;                         const int ir0 = (r0w - krlo + s) * 40 + coloff;
; #pragma unroll
;                         for (int mh = 0; mh < 2; ++mh) {
;                             s16x4 lo[4], hi[4];
; #pragma unroll
;                             for (int m4 = 0; m4 < 4; ++m4) { const int mt = mh * 4 + m4, r0_ = ir0 + 4 * kg + trq, r1_ = ir0 + 16 + 4 * kg + trq, ch_ = 2 * mt + (trp >> 1);
;                                 lo[m4] = tr_read_b64(IMG + vimg_off(r0_, ch_) + 8u * (trp & 1)); hi[m4] = tr_read_b64(IMG + vimg_off(r1_, ch_) + 8u * (trp & 1)); }
;                             asm volatile("s_waitcnt lgkmcnt(0)" ::: "memory"); __builtin_amdgcn_sched_barrier(0);
; #pragma unroll
;                             for (int m4 = 0; m4 < 4; ++m4) { const int mt = mh * 4 + m4; const bf16x8 va = (bf16x8){lo[m4][0], lo[m4][1], lo[m4][2], lo[m4][3], hi[m4][0], hi[m4][1], hi[m4][2], hi[m4][3]};
;                                 acc[mt] = __builtin_amdgcn_mfma_f32_16x16x32_bf16(va, pbf[s], acc[mt], 0, 0, 0); }
	v_bitop3_b32 v116, v146, v118, v147 bitop3:0x36
	v_mfma_f32_16x16x32_bf16 v[80:83], v[80:83], v[72:75], v[84:87]
	v_lshl_add_u32 v116, v116, 4, v148
	ds_read_b64_tr_b16 v[84:85], v116
	v_mfma_f32_16x16x32_bf16 v[96:99], v[112:115], v[72:75], v[96:99]
	s_nop 0
	v_bitop3_b32 v86, v138, v118, v139 bitop3:0x36
	v_lshl_add_u32 v86, v86, 4, v111
	v_bitop3_b32 v112, v146, v119, v147 bitop3:0x36
	ds_read_b64_tr_b16 v[86:87], v86
	v_lshl_add_u32 v112, v112, 4, v148
	v_bitop3_b32 v114, v138, v119, v139 bitop3:0x36
	ds_read_b64_tr_b16 v[112:113], v112
	v_lshl_add_u32 v114, v114, 4, v111
	v_mfma_f32_16x16x32_bf16 v[116:119], v[134:137], v[72:75], v[126:129]
	ds_read_b64_tr_b16 v[114:115], v114
	v_mfma_f32_16x16x32_bf16 v[100:103], v[130:133], v[72:75], v[100:103]
	s_nop 1
	v_bitop3_b32 v126, v146, v120, v147 bitop3:0x36
	v_lshl_add_u32 v126, v126, 4, v148
	v_bitop3_b32 v120, v138, v120, v139 bitop3:0x36
	ds_read_b64_tr_b16 v[126:127], v126
	v_lshl_add_u32 v120, v120, 4, v111
	ds_read_b64_tr_b16 v[128:129], v120
	v_bitop3_b32 v120, v146, v121, v147 bitop3:0x36
	v_lshl_add_u32 v120, v120, 4, v148
	ds_read_b64_tr_b16 v[130:131], v120
	v_bitop3_b32 v120, v138, v121, v139 bitop3:0x36
	v_lshl_add_u32 v111, v120, 4, v111
	ds_read_b64_tr_b16 v[132:133], v111
	s_waitcnt lgkmcnt(0)
; #define GAS __attribute__((address_space(1)))
; __device__ __forceinline__ unsigned pk2(float lo, float hi) { return f2bf(lo) | (f2bf(hi) << 16); }
; template <int L>
; __device__ __forceinline__ void layer_body(const Args& args, LAS unsigned char* lds, const int wave, const int G, const int gw, const int NGW, const int lo, const int hi,
;                                            unsigned char* const ws_kernel, const XcdBarrier& bar, int& pid) {
;     ...
;                             for (int m4 = 0; m4 < 4; ++m4) { const int mt = mh * 4 + m4; const bf16x8 va = (bf16x8){lo[m4][0], lo[m4][1], lo[m4][2], lo[m4][3], hi[m4][0], hi[m4][1], hi[m4][2], hi[m4][3]};
;                                 acc[mt] = __builtin_amdgcn_mfma_f32_16x16x32_bf16(va, pbf[s], acc[mt], 0, 0, 0); }
;                         }
;                     }
;                     const float inv = 1.0f / sum;
;                     GAS bf16* op = (GAS bf16*)(obuf + (size_t)(b * SEQ + r * 64 + c) * D + h * HD + 4 * kg);
; #pragma unroll
;                     for (int mt = 0; mt < 8; ++mt) { v2u w; w.x = pk2(acc[mt][0] * inv, acc[mt][1] * inv); w.y = pk2(acc[mt][2] * inv, acc[mt][3] * inv); *(GAS v2u*)(op + 16 * mt) = w; }
	v_div_scale_f32 v111, s[6:7], v104, v104, 1.0
	v_rcp_f32_e32 v120, v111
	v_mfma_f32_16x16x32_bf16 v[84:87], v[84:87], v[72:75], v[88:91]
	s_lshl_b32 s6, s14, 6
	s_add_i32 s6, s6, s60
	s_lshl_b32 s60, s36, 1
	v_fma_f32 v88, -v111, v120, 1.0
	v_fmac_f32_e32 v120, v88, v120
	v_mfma_f32_16x16x32_bf16 v[88:91], v[112:115], v[72:75], v[92:95]
	v_div_scale_f32 v112, vcc, 1.0, v104, 1.0
	v_mul_f32_e32 v113, v112, v120
	v_fma_f32 v114, -v111, v113, v112
	v_mfma_f32_16x16x32_bf16 v[92:95], v[126:129], v[72:75], v[122:125]
	v_fmac_f32_e32 v113, v114, v120
	v_fma_f32 v111, -v111, v113, v112
	s_add_i32 s84, s84, s82
	v_mfma_f32_16x16x32_bf16 v[72:75], v[130:133], v[72:75], v[76:79]
	s_add_i32 s96, s96, s92
	s_nop 1
	v_or_b32_e32 v78, s6, v109
	v_ashrrev_i32_e32 v79, 31, v78
	v_div_fmas_f32 v76, v111, v120, v113
	v_lshlrev_b64 v[78:79], 12, v[78:79]
	v_div_fixup_f32 v76, v76, v104, 1.0
	v_lshl_add_u64 v[78:79], s[4:5], 0, v[78:79]
	v_mov_b32_e32 v111, v82
	v_mov_b32_e32 v82, v81
	v_lshl_add_u64 v[78:79], v[78:79], 0, s[60:61]
	v_lshlrev_b32_e32 v104, 1, v110
	v_mov_b32_e32 v110, v80
	v_pk_mul_f32 v[80:81], v[76:77], v[82:83] op_sel_hi:[0,1]
	v_lshl_add_u64 v[78:79], v[78:79], 0, v[104:105]
	v_pk_mul_f32 v[110:111], v[76:77], v[110:111] op_sel_hi:[0,1]
	v_and_b32_sdwa v83, v81, v108 dst_sel:DWORD dst_unused:UNUSED_PAD src0_sel:WORD_1 src1_sel:DWORD
	v_and_b32_sdwa v77, v111, v108 dst_sel:DWORD dst_unused:UNUSED_PAD src0_sel:WORD_1 src1_sel:DWORD
	v_add3_u32 v81, v81, v83, s23
	v_add3_u32 v77, v111, v77, s23
	v_and_b32_e32 v81, 0xffff0000, v81
	v_or_b32_sdwa v81, v81, v77 dst_sel:DWORD dst_unused:UNUSED_PAD src0_sel:DWORD src1_sel:WORD_1
	v_cvt_pk_bf16_f32 v80, v110, v80
	global_store_dwordx2 v[78:79], v[80:81], off
	v_mov_b32_e32 v80, v96
	v_mov_b32_e32 v81, v98
	v_pk_mul_f32 v[80:81], v[76:77], v[80:81] op_sel_hi:[0,1]
	v_mov_b32_e32 v98, v97
	v_pk_mul_f32 v[82:83], v[76:77], v[98:99] op_sel_hi:[0,1]
	v_and_b32_sdwa v77, v81, v108 dst_sel:DWORD dst_unused:UNUSED_PAD src0_sel:WORD_1 src1_sel:DWORD
	v_add3_u32 v77, v81, v77, s23
	v_and_b32_sdwa v81, v83, v108 dst_sel:DWORD dst_unused:UNUSED_PAD src0_sel:WORD_1 src1_sel:DWORD
	v_add3_u32 v81, v83, v81, s23
	v_and_b32_e32 v81, 0xffff0000, v81
	v_or_b32_sdwa v81, v81, v77 dst_sel:DWORD dst_unused:UNUSED_PAD src0_sel:DWORD src1_sel:WORD_1
	v_cvt_pk_bf16_f32 v80, v80, v82
	global_store_dwordx2 v[78:79], v[80:81], off offset:32
	v_mov_b32_e32 v80, v100
	v_mov_b32_e32 v81, v102
	v_pk_mul_f32 v[80:81], v[76:77], v[80:81] op_sel_hi:[0,1]
	v_mov_b32_e32 v102, v101
	v_pk_mul_f32 v[82:83], v[76:77], v[102:103] op_sel_hi:[0,1]
	v_and_b32_sdwa v77, v81, v108 dst_sel:DWORD dst_unused:UNUSED_PAD src0_sel:WORD_1 src1_sel:DWORD
	v_add3_u32 v77, v81, v77, s23
	v_and_b32_sdwa v81, v83, v108 dst_sel:DWORD dst_unused:UNUSED_PAD src0_sel:WORD_1 src1_sel:DWORD
	v_add3_u32 v81, v83, v81, s23
	v_and_b32_e32 v81, 0xffff0000, v81
	v_or_b32_sdwa v81, v81, v77 dst_sel:DWORD dst_unused:UNUSED_PAD src0_sel:DWORD src1_sel:WORD_1
	v_cvt_pk_bf16_f32 v80, v80, v82
	global_store_dwordx2 v[78:79], v[80:81], off offset:64
	v_mov_b32_e32 v80, v116
	v_mov_b32_e32 v81, v118
	v_pk_mul_f32 v[80:81], v[76:77], v[80:81] op_sel_hi:[0,1]
	v_mov_b32_e32 v118, v117
	v_pk_mul_f32 v[82:83], v[76:77], v[118:119] op_sel_hi:[0,1]
	v_and_b32_sdwa v77, v81, v108 dst_sel:DWORD dst_unused:UNUSED_PAD src0_sel:WORD_1 src1_sel:DWORD
	v_add3_u32 v77, v81, v77, s23
	v_and_b32_sdwa v81, v83, v108 dst_sel:DWORD dst_unused:UNUSED_PAD src0_sel:WORD_1 src1_sel:DWORD
	v_add3_u32 v81, v83, v81, s23
	v_and_b32_e32 v81, 0xffff0000, v81
	v_or_b32_sdwa v81, v81, v77 dst_sel:DWORD dst_unused:UNUSED_PAD src0_sel:DWORD src1_sel:WORD_1
	v_cvt_pk_bf16_f32 v80, v80, v82
	global_store_dwordx2 v[78:79], v[80:81], off offset:96
	v_mov_b32_e32 v80, v84
	v_mov_b32_e32 v81, v86
	v_pk_mul_f32 v[80:81], v[76:77], v[80:81] op_sel_hi:[0,1]
	v_mov_b32_e32 v86, v85
	v_pk_mul_f32 v[82:83], v[76:77], v[86:87] op_sel_hi:[0,1]
	v_and_b32_sdwa v77, v81, v108 dst_sel:DWORD dst_unused:UNUSED_PAD src0_sel:WORD_1 src1_sel:DWORD
	v_add3_u32 v77, v81, v77, s23
	v_and_b32_sdwa v81, v83, v108 dst_sel:DWORD dst_unused:UNUSED_PAD src0_sel:WORD_1 src1_sel:DWORD
	v_add3_u32 v81, v83, v81, s23
	v_and_b32_e32 v81, 0xffff0000, v81
	v_or_b32_sdwa v81, v81, v77 dst_sel:DWORD dst_unused:UNUSED_PAD src0_sel:DWORD src1_sel:WORD_1
	v_cvt_pk_bf16_f32 v80, v80, v82
	global_store_dwordx2 v[78:79], v[80:81], off offset:128
	v_mov_b32_e32 v80, v88
	v_mov_b32_e32 v81, v90
	v_pk_mul_f32 v[80:81], v[76:77], v[80:81] op_sel_hi:[0,1]
	v_mov_b32_e32 v90, v89
	v_pk_mul_f32 v[82:83], v[76:77], v[90:91] op_sel_hi:[0,1]
	v_and_b32_sdwa v77, v81, v108 dst_sel:DWORD dst_unused:UNUSED_PAD src0_sel:WORD_1 src1_sel:DWORD
	v_add3_u32 v77, v81, v77, s23
	v_and_b32_sdwa v81, v83, v108 dst_sel:DWORD dst_unused:UNUSED_PAD src0_sel:WORD_1 src1_sel:DWORD
	v_add3_u32 v81, v83, v81, s23
	v_and_b32_e32 v81, 0xffff0000, v81
	v_or_b32_sdwa v81, v81, v77 dst_sel:DWORD dst_unused:UNUSED_PAD src0_sel:DWORD src1_sel:WORD_1
	v_cvt_pk_bf16_f32 v80, v80, v82
	global_store_dwordx2 v[78:79], v[80:81], off offset:160
	v_mov_b32_e32 v80, v92
	v_mov_b32_e32 v81, v94
	v_pk_mul_f32 v[80:81], v[76:77], v[80:81] op_sel_hi:[0,1]
	v_mov_b32_e32 v94, v93
	v_pk_mul_f32 v[82:83], v[76:77], v[94:95] op_sel_hi:[0,1]
	v_and_b32_sdwa v77, v81, v108 dst_sel:DWORD dst_unused:UNUSED_PAD src0_sel:WORD_1 src1_sel:DWORD
	v_add3_u32 v77, v81, v77, s23
	v_and_b32_sdwa v81, v83, v108 dst_sel:DWORD dst_unused:UNUSED_PAD src0_sel:WORD_1 src1_sel:DWORD
	v_add3_u32 v81, v83, v81, s23
	v_and_b32_e32 v81, 0xffff0000, v81
	v_or_b32_sdwa v81, v81, v77 dst_sel:DWORD dst_unused:UNUSED_PAD src0_sel:DWORD src1_sel:WORD_1
	v_cvt_pk_bf16_f32 v80, v80, v82
	global_store_dwordx2 v[78:79], v[80:81], off offset:192
	v_mov_b32_e32 v81, v74
	v_mov_b32_e32 v74, v73
	v_mov_b32_e32 v80, v72
	v_pk_mul_f32 v[72:73], v[76:77], v[74:75] op_sel_hi:[0,1]
	v_pk_mul_f32 v[80:81], v[76:77], v[80:81] op_sel_hi:[0,1]
	v_cvt_pk_bf16_f32 v73, v81, v73
	v_cvt_pk_bf16_f32 v72, v80, v72
	s_andn2_b64 vcc, exec, s[0:1]
	global_store_dwordx2 v[78:79], v[72:73], off offset:224
	s_barrier
	s_cbranch_vccz .LBB0_976

; #define LAS __attribute__((address_space(3)))
; template <int L>
; __device__ __forceinline__ void layer_body(const Args& args, LAS unsigned char* lds, const int wave, const int G, const int gw, const int NGW, const int lo, const int hi,
;                                            unsigned char* const ws_kernel, const XcdBarrier& bar, int& pid) {
;     ...
;                     for (int t = 0; t < 10; ++t) {
;                         const int T = wave + t, Tc = min(T, 15);
;                         const unsigned ka = Kimg + (unsigned)((16 * Tc + qi) * KPITCH + 16 * kg);
;                         f32x4 a = (f32x4){0.f, 0.f, 0.f, 0.f};
; #pragma unroll
;                         for (int ks = 0; ks < 4; ++ks) a = __builtin_amdgcn_mfma_f32_16x16x32_bf16(*(const LAS bf16x8*)(size_t)(ka + 64 * ks), qfn[ks], a, 0, 0, 0);
; #pragma unroll
;                         for (int j = 0; j < 4; ++j) { const int m = ms - 64 + 16 * T + 4 * kg + j, dd = m - mq; const bool valid = (m >= 0) && (m < Lc) && (dd >= -64) && (dd <= 64);
;                             sc[t][j] = valid ? a[j] * scale_log2 : -1e30f; }
;                         __builtin_amdgcn_sched_barrier(0);
;                     }
.LBB0_1714:
	s_add_i32 s2, s83, s39
	v_or_b32_e32 v112, s2, v120
	v_sub_u32_e32 v136, v112, v121
	v_add_u32_e32 v136, 64, v136
	v_cmp_gt_i32_e32 vcc, s82, v112
	v_cmp_gt_u32_e64 s[2:3], s59, v136
	v_mul_f32_e32 v108, 0x3e0293ee, v108
	s_and_b64 vcc, vcc, s[2:3]
	v_or_b32_e32 v136, 1, v112
	v_cndmask_b32_e32 v108, v116, v108, vcc
	v_cmp_gt_i32_e32 vcc, s82, v136
	v_sub_u32_e32 v136, v136, v121
	v_add_u32_e32 v136, 64, v136
	v_cmp_gt_u32_e64 s[2:3], s59, v136
	v_mul_f32_e32 v109, 0x3e0293ee, v109
	s_and_b64 vcc, vcc, s[2:3]
	v_or_b32_e32 v136, 2, v112
	v_cndmask_b32_e32 v109, v116, v109, vcc
	v_cmp_gt_i32_e32 vcc, s82, v136
	v_sub_u32_e32 v136, v136, v121
	v_add_u32_e32 v136, 64, v136
	v_cmp_gt_u32_e64 s[2:3], s59, v136
	v_mul_f32_e32 v110, 0x3e0293ee, v110
	s_and_b64 vcc, vcc, s[2:3]
	v_or_b32_e32 v112, 3, v112
	v_cndmask_b32_e32 v110, v116, v110, vcc
	v_cmp_gt_i32_e32 vcc, s82, v112
	v_sub_u32_e32 v112, v112, v121
	v_add_u32_e32 v112, 64, v112
	v_cmp_gt_u32_e64 s[2:3], s59, v112
	s_and_b64 vcc, vcc, s[2:3]
	s_add_i32 s2, s83, s41
	v_or_b32_e32 v112, s2, v120
	v_sub_u32_e32 v136, v112, v121
	v_mul_f32_e32 v111, 0x3e0293ee, v111
	v_add_u32_e32 v136, 64, v136
	v_cndmask_b32_e32 v111, v116, v111, vcc
	v_cmp_gt_i32_e32 vcc, s82, v112
	v_cmp_gt_u32_e64 s[2:3], s59, v136
	v_mul_f32_e32 v104, 0x3e0293ee, v104
	s_and_b64 vcc, vcc, s[2:3]
	v_or_b32_e32 v136, 1, v112
	v_cndmask_b32_e32 v104, v116, v104, vcc
	v_cmp_gt_i32_e32 vcc, s82, v136
	v_sub_u32_e32 v136, v136, v121
	v_add_u32_e32 v136, 64, v136
	v_cmp_gt_u32_e64 s[2:3], s59, v136
	v_mul_f32_e32 v105, 0x3e0293ee, v105
	s_and_b64 vcc, vcc, s[2:3]
	v_or_b32_e32 v136, 2, v112
	v_cndmask_b32_e32 v105, v116, v105, vcc
	v_cmp_gt_i32_e32 vcc, s82, v136
	v_sub_u32_e32 v136, v136, v121
	v_add_u32_e32 v136, 64, v136
	v_cmp_gt_u32_e64 s[2:3], s59, v136
	v_mul_f32_e32 v106, 0x3e0293ee, v106
	s_and_b64 vcc, vcc, s[2:3]
	v_or_b32_e32 v112, 3, v112
	v_cndmask_b32_e32 v106, v116, v106, vcc
	v_cmp_gt_i32_e32 vcc, s82, v112
	v_sub_u32_e32 v112, v112, v121
	v_add_u32_e32 v112, 64, v112
	v_cmp_gt_u32_e64 s[2:3], s59, v112
	s_and_b64 vcc, vcc, s[2:3]
	s_add_i32 s2, s83, s43
	v_or_b32_e32 v112, s2, v120
	v_sub_u32_e32 v136, v112, v121
	v_mul_f32_e32 v107, 0x3e0293ee, v107
	v_add_u32_e32 v136, 64, v136
	v_cndmask_b32_e32 v107, v116, v107, vcc
	v_cmp_gt_i32_e32 vcc, s82, v112
	v_cmp_gt_u32_e64 s[2:3], s59, v136
	v_mul_f32_e32 v100, 0x3e0293ee, v100
	s_and_b64 vcc, vcc, s[2:3]
	v_or_b32_e32 v136, 1, v112
	v_cndmask_b32_e32 v100, v116, v100, vcc
	v_cmp_gt_i32_e32 vcc, s82, v136
	v_sub_u32_e32 v136, v136, v121
	v_add_u32_e32 v136, 64, v136
	v_cmp_gt_u32_e64 s[2:3], s59, v136
	v_mul_f32_e32 v101, 0x3e0293ee, v101
	s_and_b64 vcc, vcc, s[2:3]
	v_or_b32_e32 v136, 2, v112
	v_cndmask_b32_e32 v101, v116, v101, vcc
	v_cmp_gt_i32_e32 vcc, s82, v136
	v_sub_u32_e32 v136, v136, v121
	v_add_u32_e32 v136, 64, v136
	v_cmp_gt_u32_e64 s[2:3], s59, v136
	v_mul_f32_e32 v102, 0x3e0293ee, v102
	s_and_b64 vcc, vcc, s[2:3]
	v_or_b32_e32 v112, 3, v112
	v_cndmask_b32_e32 v102, v116, v102, vcc
	v_cmp_gt_i32_e32 vcc, s82, v112
	v_sub_u32_e32 v112, v112, v121
	v_add_u32_e32 v112, 64, v112
	v_cmp_gt_u32_e64 s[2:3], s59, v112
	s_and_b64 vcc, vcc, s[2:3]
	s_add_i32 s2, s83, s45
	v_or_b32_e32 v112, s2, v120
	v_sub_u32_e32 v136, v112, v121
	v_mul_f32_e32 v103, 0x3e0293ee, v103
	v_add_u32_e32 v136, 64, v136
	v_cndmask_b32_e32 v103, v116, v103, vcc
	v_cmp_gt_i32_e32 vcc, s82, v112
	v_cmp_gt_u32_e64 s[2:3], s59, v136
	v_mul_f32_e32 v96, 0x3e0293ee, v96
	s_and_b64 vcc, vcc, s[2:3]
	v_or_b32_e32 v136, 1, v112
	v_cndmask_b32_e32 v96, v116, v96, vcc
	v_cmp_gt_i32_e32 vcc, s82, v136
	v_sub_u32_e32 v136, v136, v121
	v_add_u32_e32 v136, 64, v136
	v_cmp_gt_u32_e64 s[2:3], s59, v136
	v_mul_f32_e32 v97, 0x3e0293ee, v97
	s_and_b64 vcc, vcc, s[2:3]
	v_or_b32_e32 v136, 2, v112
	v_cndmask_b32_e32 v97, v116, v97, vcc
	v_cmp_gt_i32_e32 vcc, s82, v136
	v_sub_u32_e32 v136, v136, v121
	v_add_u32_e32 v136, 64, v136
	v_cmp_gt_u32_e64 s[2:3], s59, v136
	v_mul_f32_e32 v98, 0x3e0293ee, v98
	s_and_b64 vcc, vcc, s[2:3]
	v_or_b32_e32 v112, 3, v112
	v_cndmask_b32_e32 v98, v116, v98, vcc
	v_cmp_gt_i32_e32 vcc, s82, v112
	v_sub_u32_e32 v112, v112, v121
	v_add_u32_e32 v112, 64, v112
	v_cmp_gt_u32_e64 s[2:3], s59, v112
	s_and_b64 vcc, vcc, s[2:3]
	s_add_i32 s2, s83, s47
	v_or_b32_e32 v112, s2, v120
	v_sub_u32_e32 v136, v112, v121
	v_mul_f32_e32 v99, 0x3e0293ee, v99
	v_add_u32_e32 v136, 64, v136
	v_cndmask_b32_e32 v99, v116, v99, vcc
	v_cmp_gt_i32_e32 vcc, s82, v112
	v_cmp_gt_u32_e64 s[2:3], s59, v136
	v_mul_f32_e32 v92, 0x3e0293ee, v92
	s_and_b64 vcc, vcc, s[2:3]
	v_or_b32_e32 v136, 1, v112
	v_cndmask_b32_e32 v92, v116, v92, vcc
	v_cmp_gt_i32_e32 vcc, s82, v136
	v_sub_u32_e32 v136, v136, v121
	v_add_u32_e32 v136, 64, v136
	v_cmp_gt_u32_e64 s[2:3], s59, v136
	v_mul_f32_e32 v93, 0x3e0293ee, v93
	s_and_b64 vcc, vcc, s[2:3]
	v_or_b32_e32 v136, 2, v112
	v_cndmask_b32_e32 v93, v116, v93, vcc
	v_cmp_gt_i32_e32 vcc, s82, v136
	v_sub_u32_e32 v136, v136, v121
	v_add_u32_e32 v136, 64, v136
	v_cmp_gt_u32_e64 s[2:3], s59, v136
	v_mul_f32_e32 v94, 0x3e0293ee, v94
	s_and_b64 vcc, vcc, s[2:3]
	v_or_b32_e32 v112, 3, v112
	v_cndmask_b32_e32 v94, v116, v94, vcc
	v_cmp_gt_i32_e32 vcc, s82, v112
	v_sub_u32_e32 v112, v112, v121
	v_add_u32_e32 v112, 64, v112
	s_add_i32 s83, s83, s49
	v_cmp_gt_u32_e64 s[2:3], s59, v112
	v_or_b32_e32 v112, s83, v120
	v_sub_u32_e32 v136, v112, v121
	v_mul_f32_e32 v95, 0x3e0293ee, v95
	s_and_b64 vcc, vcc, s[2:3]
	v_add_u32_e32 v136, 64, v136
	v_cndmask_b32_e32 v95, v116, v95, vcc
	v_cmp_gt_i32_e32 vcc, s82, v112
	v_cmp_gt_u32_e64 s[2:3], s59, v136
	v_mul_f32_e32 v88, 0x3e0293ee, v88
; __device__ __forceinline__ unsigned pk2(float lo, float hi) { return f2bf(lo) | (f2bf(hi) << 16); }
; template <int L>
; __device__ __forceinline__ void layer_body(const Args& args, LAS unsigned char* lds, const int wave, const int G, const int gw, const int NGW, const int lo, const int hi,
;                                            unsigned char* const ws_kernel, const XcdBarrier& bar, int& pid) {
;     ...
;                         for (int j = 0; j < 4; ++j) { const int m = ms - 64 + 16 * T + 4 * kg + j, dd = m - mq; const bool valid = (m >= 0) && (m < Lc) && (dd >= -64) && (dd <= 64);
;                             sc[t][j] = valid ? a[j] * scale_log2 : -1e30f; }
;                         __builtin_amdgcn_sched_barrier(0);
;                     }
;                     if (unit + GH < UEND) DSW_LOADQ(unit + GH);
;                     float mx = -1e30f;
; #pragma unroll
;                     for (int t = 0; t < 10; ++t)
; #pragma unroll
;                         for (int j = 0; j < 4; ++j) mx = fmaxf(mx, sc[t][j]);
;                     mx = fmaxf(mx, __shfl_xor(mx, 16)); mx = fmaxf(mx, __shfl_xor(mx, 32));
;                     float sum = 0.f;
; #pragma unroll
;                     for (int t = 0; t < 10; ++t)
; #pragma unroll
;                         for (int j = 0; j < 4; ++j) { sc[t][j] = __builtin_amdgcn_exp2f(sc[t][j] - mx); sum += sc[t][j]; }
;                     sum += __shfl_xor(sum, 16); sum += __shfl_xor(sum, 32);
;                     f32x4 acc[8];
; #pragma unroll
;                     for (int mt = 0; mt < 8; ++mt) acc[mt] = (f32x4){0.f, 0.f, 0.f, 0.f};
;                     const int trq = (lane & 15) >> 2, trp = lane & 3;
; #pragma unroll
;                     for (int s = 0; s < 5; ++s) {
;                         const int T0 = min(wave + 2 * s, 15), T1 = min(wave + 2 * s + 1, 15);
;                         bf16x8 pb; { const f32x4 p0 = sc[2 * s], p1 = sc[2 * s + 1]; v4u w; w.x = pk2(p0[0], p0[1]); w.y = pk2(p0[2], p0[3]); w.z = pk2(p1[0], p1[1]); w.w = pk2(p1[2], p1[3]); pb = __builtin_bit_cast(bf16x8, w); }
	s_and_b64 vcc, vcc, s[2:3]
	v_cndmask_b32_e32 v136, v116, v88, vcc
	v_or_b32_e32 v88, 1, v112
	v_cmp_gt_i32_e32 vcc, s82, v88
	v_sub_u32_e32 v88, v88, v121
	v_add_u32_e32 v88, 64, v88
	v_cmp_gt_u32_e64 s[2:3], s59, v88
	v_mul_f32_e32 v88, 0x3e0293ee, v89
	s_and_b64 vcc, vcc, s[2:3]
	v_cndmask_b32_e32 v89, v116, v88, vcc
	v_or_b32_e32 v88, 2, v112
	v_cmp_gt_i32_e32 vcc, s82, v88
	v_sub_u32_e32 v88, v88, v121
	v_add_u32_e32 v88, 64, v88
	v_cmp_gt_u32_e64 s[2:3], s59, v88
	v_mul_f32_e32 v88, 0x3e0293ee, v90
	s_and_b64 vcc, vcc, s[2:3]
	v_cndmask_b32_e32 v137, v116, v88, vcc
	v_or_b32_e32 v88, 3, v112
	v_cmp_gt_i32_e32 vcc, s82, v88
	v_sub_u32_e32 v88, v88, v121
	v_add_u32_e32 v88, 64, v88
	v_cmp_gt_u32_e64 s[2:3], s59, v88
	v_mul_f32_e32 v88, 0x3e0293ee, v91
	s_and_b64 vcc, vcc, s[2:3]
	v_cndmask_b32_e32 v112, v116, v88, vcc
	v_sub_u32_e32 v88, v135, v121
	v_cmp_gt_i32_e32 vcc, s82, v135
	v_add_u32_e32 v88, 64, v88
	v_cmp_gt_u32_e64 s[2:3], s59, v88
	s_and_b64 s[4:5], s[76:77], vcc
	v_mul_f32_e32 v86, 0x3e0293ee, v86
	s_and_b64 vcc, s[4:5], s[2:3]
	v_sub_u32_e32 v88, v133, v121
	v_cndmask_b32_e32 v86, v116, v86, vcc
	v_cmp_gt_i32_e32 vcc, s82, v133
	v_add_u32_e32 v88, 64, v88
	v_cmp_gt_u32_e64 s[2:3], s59, v88
	s_and_b64 s[4:5], s[74:75], vcc
	v_mul_f32_e32 v84, 0x3e0293ee, v84
	s_and_b64 vcc, s[4:5], s[2:3]
	v_cndmask_b32_e32 v88, v116, v84, vcc
	v_sub_u32_e32 v84, v129, v121
	v_cmp_gt_i32_e32 vcc, s82, v129
	v_add_u32_e32 v84, 64, v84
	v_cmp_gt_u32_e64 s[2:3], s59, v84
	s_and_b64 s[4:5], s[72:73], vcc
	v_mul_f32_e32 v82, 0x3e0293ee, v82
	s_and_b64 vcc, s[4:5], s[2:3]
	v_cndmask_b32_e32 v90, v116, v82, vcc
	v_sub_u32_e32 v82, v127, v121
	v_cmp_gt_i32_e32 vcc, s82, v127
	v_add_u32_e32 v82, 64, v82
	v_cmp_gt_u32_e64 s[2:3], s59, v82
	s_and_b64 s[4:5], s[70:71], vcc
	v_mul_f32_e32 v80, 0x3e0293ee, v80
	s_and_b64 vcc, s[4:5], s[2:3]
	v_cndmask_b32_e32 v91, v116, v80, vcc
	s_mov_b32 s2, 0xf149f2ca
	v_max3_f32 v80, v91, s2, v125
	v_max3_f32 v80, v80, v124, v126
	v_max3_f32 v80, v80, v90, v81
	v_max3_f32 v80, v80, v128, v83
	v_max3_f32 v80, v80, v88, v131
	v_max3_f32 v80, v80, v130, v132
	v_max3_f32 v80, v80, v86, v85
	v_max3_f32 v80, v80, v134, v87
	v_max3_f32 v80, v80, v108, v109
	v_max3_f32 v80, v80, v110, v111
	v_max3_f32 v80, v80, v104, v105
	v_max3_f32 v80, v80, v106, v107
	v_max3_f32 v80, v80, v100, v101
	v_max3_f32 v80, v80, v102, v103
	v_max3_f32 v80, v80, v96, v97
	v_max3_f32 v80, v80, v98, v99
	v_max3_f32 v80, v80, v92, v93
	v_max3_f32 v80, v80, v94, v95
	v_max3_f32 v80, v80, v136, v89
	v_and_b32_e32 v84, 64, v115
	v_max3_f32 v82, v80, v137, v112
	v_xor_b32_e32 v80, 16, v115
	v_add_u32_e32 v84, 64, v84
	v_cmp_lt_i32_e32 vcc, v80, v84
	s_sub_i32 s2, 4, s67
	s_and_b32 s4, s12, 15
	v_cndmask_b32_e32 v80, v115, v80, vcc
	v_lshlrev_b32_e32 v80, 2, v80
	ds_bpermute_b32 v127, v80, v82
	s_lshr_b32 s2, s81, s2
	s_waitcnt lgkmcnt(0)
	v_max_f32_e32 v127, v127, v127
	v_max_f32_e32 v82, v82, v127
	v_xor_b32_e32 v127, 32, v115
	v_cmp_lt_i32_e32 vcc, v127, v84
	s_nop 1
	v_cndmask_b32_e32 v84, v115, v127, vcc
	v_lshlrev_b32_e32 v84, 2, v84
	ds_bpermute_b32 v127, v84, v82
	s_waitcnt lgkmcnt(0)
	v_max_f32_e32 v127, v127, v127
	v_max_f32_e32 v82, v82, v127
	v_sub_f32_e32 v81, v81, v82
	v_exp_f32_e32 v133, v81
	v_sub_f32_e32 v81, v128, v82
	v_exp_f32_e32 v128, v81
	v_sub_f32_e32 v81, v83, v82
	v_exp_f32_e32 v135, v81
	v_sub_f32_e32 v81, v88, v82
	v_exp_f32_e32 v150, v81
	v_sub_f32_e32 v81, v131, v82
	v_exp_f32_e32 v151, v81
	v_sub_f32_e32 v81, v130, v82
	v_exp_f32_e32 v152, v81
	v_sub_f32_e32 v81, v132, v82
	v_exp_f32_e32 v153, v81
	v_sub_f32_e32 v81, v86, v82
	v_exp_f32_e32 v154, v81
	v_sub_f32_e32 v81, v85, v82
	v_exp_f32_e32 v155, v81
	v_sub_f32_e32 v81, v134, v82
	v_exp_f32_e32 v156, v81
	v_sub_f32_e32 v81, v87, v82
	v_exp_f32_e32 v157, v81
	v_sub_f32_e32 v81, v108, v82
	v_exp_f32_e32 v166, v81
	v_sub_f32_e32 v81, v109, v82
	v_exp_f32_e32 v167, v81
	v_sub_f32_e32 v81, v110, v82
	v_exp_f32_e32 v110, v81
	v_sub_f32_e32 v81, v111, v82
	v_sub_f32_e32 v91, v91, v82
	v_exp_f32_e32 v111, v81
	v_sub_f32_e32 v81, v104, v82
	v_exp_f32_e32 v127, v91
	v_sub_f32_e32 v91, v125, v82
	v_exp_f32_e32 v168, v81
	v_sub_f32_e32 v81, v105, v82
	v_exp_f32_e32 v125, v91
	v_sub_f32_e32 v91, v124, v82
	v_exp_f32_e32 v169, v81
	v_sub_f32_e32 v81, v106, v82
	v_exp_f32_e32 v124, v91
	v_sub_f32_e32 v91, v126, v82
	v_exp_f32_e32 v170, v81
	v_sub_f32_e32 v81, v107, v82
	v_sub_f32_e32 v83, v93, v82
	v_exp_f32_e32 v126, v91
	v_sub_f32_e32 v90, v90, v82
	v_exp_f32_e32 v171, v81
	v_sub_f32_e32 v81, v100, v82
	v_exp_f32_e32 v88, v83
	v_sub_f32_e32 v83, v94, v82
	v_exp_f32_e32 v129, v90
	v_exp_f32_e32 v172, v81
	v_sub_f32_e32 v81, v101, v82
	v_exp_f32_e32 v85, v83
	v_sub_f32_e32 v83, v95, v82
	v_add_f32_e32 v95, 0, v127
	v_exp_f32_e32 v173, v81
	v_sub_f32_e32 v81, v102, v82
	v_add_f32_e32 v95, v125, v95
	v_exp_f32_e32 v174, v81
	v_sub_f32_e32 v81, v103, v82
	v_add_f32_e32 v95, v124, v95
	v_exp_f32_e32 v175, v81
	v_sub_f32_e32 v81, v96, v82
	v_exp_f32_e32 v90, v83
	v_sub_f32_e32 v83, v136, v82
	v_add_f32_e32 v95, v126, v95
	v_exp_f32_e32 v176, v81
	v_sub_f32_e32 v81, v97, v82
	v_exp_f32_e32 v87, v83
	v_sub_f32_e32 v83, v89, v82
	v_add_f32_e32 v95, v129, v95
	v_exp_f32_e32 v177, v81
	v_sub_f32_e32 v81, v98, v82
	v_exp_f32_e32 v91, v83
	v_sub_f32_e32 v83, v137, v82
	v_add_f32_e32 v95, v133, v95
	v_exp_f32_e32 v178, v81
	v_sub_f32_e32 v81, v99, v82
	v_exp_f32_e32 v89, v83
	v_sub_f32_e32 v83, v112, v82
	v_add_f32_e32 v95, v128, v95
	v_exp_f32_e32 v179, v81
	v_sub_f32_e32 v81, v92, v82
	v_exp_f32_e32 v92, v83
	v_lshrrev_b32_e32 v83, 2, v123
	v_add_f32_e32 v158, v135, v95
	v_or_b32_e32 v93, v120, v83
; __device__ __forceinline__ unsigned pk2(float lo, float hi) { return f2bf(lo) | (f2bf(hi) << 16); }
; __device__ __forceinline__ s16x4 tr_read_b64(unsigned addr) { s16x4 r; asm volatile("ds_read_b64_tr_b16 %0, %1" : "=v"(r) : "v"(addr) : "memory"); return r; }
; template <int L>
; __device__ __forceinline__ void layer_body(const Args& args, LAS unsigned char* lds, const int wave, const int G, const int gw, const int NGW, const int lo, const int hi,
;                                            unsigned char* const ws_kernel, const XcdBarrier& bar, int& pid) {
;     ...
;                     for (int s = 0; s < 5; ++s) {
;                         const int T0 = min(wave + 2 * s, 15), T1 = min(wave + 2 * s + 1, 15);
;                         bf16x8 pb; { const f32x4 p0 = sc[2 * s], p1 = sc[2 * s + 1]; v4u w; w.x = pk2(p0[0], p0[1]); w.y = pk2(p0[2], p0[3]); w.z = pk2(p1[0], p1[1]); w.w = pk2(p1[2], p1[3]); pb = __builtin_bit_cast(bf16x8, w); }
; #pragma unroll
;                         for (int mh = 0; mh < 2; ++mh) {
;                             s16x4 lo[4], hi[4];
; #pragma unroll
;                             for (int m4 = 0; m4 < 4; ++m4) { const int mt = mh * 4 + m4, r0_ = 16 * T0 + 4 * kg + trq, r1_ = 16 * T1 + 4 * kg + trq, ch_ = 2 * mt + (trp >> 1);
;                                 lo[m4] = tr_read_b64(Vimg + vimg_off(r0_, ch_) + 8u * (trp & 1)); hi[m4] = tr_read_b64(Vimg + vimg_off(r1_, ch_) + 8u * (trp & 1)); }
;                             asm volatile("s_waitcnt lgkmcnt(0)" ::: "memory"); __builtin_amdgcn_sched_barrier(0);
; #pragma unroll
;                             for (int m4 = 0; m4 < 4; ++m4) { const int mt = mh * 4 + m4; const bf16x8 va = (bf16x8){lo[m4][0], lo[m4][1], lo[m4][2], lo[m4][3], hi[m4][0], hi[m4][1], hi[m4][2], hi[m4][3]};
;                                 acc[mt] = __builtin_amdgcn_mfma_f32_16x16x32_bf16(va, pb, acc[mt], 0, 0, 0); }
	v_bfe_u32 v112, v122, 1, 1
	v_and_b32_e32 v94, 12, v122
	v_lshlrev_b32_e32 v86, 3, v122
	v_and_or_b32 v86, v86, 8, s55
	v_cvt_pk_bf16_f32 v105, v128, v135
	v_cvt_pk_bf16_f32 v103, v124, v126
	v_or3_b32 v95, s14, v83, v120
	v_lshl_or_b32 v97, v93, 8, v117
	v_bitop3_b32 v93, v119, v112, v94 bitop3:0x36
	v_cvt_pk_bf16_f32 v102, v127, v125
	v_lshl_add_u32 v147, v95, 8, v86
	v_lshlrev_b32_e32 v98, 4, v93
	v_add3_u32 v148, v86, s50, v97
	v_add_u32_e32 v93, v147, v98
	v_or_b32_e32 v146, v119, v94
	ds_read_b64_tr_b16 v[106:107], v93
	v_add_u32_e32 v93, v148, v98
	ds_read_b64_tr_b16 v[108:109], v93
	v_bitop3_b32 v93, v112, v146, 2 bitop3:0x36
	v_lshlrev_b32_e32 v99, 4, v93
	v_add_u32_e32 v93, v147, v99
	ds_read_b64_tr_b16 v[122:123], v93
	v_add_u32_e32 v93, v148, v99
	ds_read_b64_tr_b16 v[124:125], v93
	v_bitop3_b32 v93, v112, v146, 4 bitop3:0x36
	v_lshlrev_b32_e32 v100, 4, v93
	v_bfe_u32 v101, v129, 16, 1
	v_add_u32_e32 v93, v147, v100
	v_bfe_u32 v96, v133, 16, 1
	v_add3_u32 v101, v129, v101, s78
	ds_read_b64_tr_b16 v[126:127], v93
	v_add_u32_e32 v93, v148, v100
	v_add3_u32 v96, v133, v96, s78
	v_lshrrev_b32_e32 v101, 16, v101
	ds_read_b64_tr_b16 v[128:129], v93
	v_bitop3_b32 v93, v112, v146, 6 bitop3:0x36
	v_and_or_b32 v104, v96, s79, v101
	v_lshlrev_b32_e32 v101, 4, v93
	v_add_u32_e32 v93, v147, v101
	ds_read_b64_tr_b16 v[130:131], v93
	v_exp_f32_e32 v81, v81
	v_add_u32_e32 v93, v148, v101
	ds_read_b64_tr_b16 v[132:133], v93
	s_waitcnt lgkmcnt(0)
	v_bitop3_b32 v93, v112, v146, 8 bitop3:0x36
	v_lshlrev_b32_e32 v94, 4, v93
	v_add_u32_e32 v93, v147, v94
	ds_read_b64_tr_b16 v[134:135], v93
	v_add_u32_e32 v93, v148, v94
	ds_read_b64_tr_b16 v[136:137], v93
	v_bitop3_b32 v93, v112, v146, 10 bitop3:0x36
	v_lshlrev_b32_e32 v95, 4, v93
	v_add_u32_e32 v93, v147, v95
	ds_read_b64_tr_b16 v[138:139], v93
	v_add_u32_e32 v93, v148, v95
	ds_read_b64_tr_b16 v[140:141], v93
	v_bitop3_b32 v93, v112, v146, 12 bitop3:0x36
	v_lshlrev_b32_e32 v96, 4, v93
	v_add_u32_e32 v93, v147, v96
	ds_read_b64_tr_b16 v[142:143], v93
	v_add_u32_e32 v93, v148, v96
	ds_read_b64_tr_b16 v[144:145], v93
	v_bitop3_b32 v93, v112, v146, 14 bitop3:0x36
	v_lshlrev_b32_e32 v93, 4, v93
	v_add_u32_e32 v112, v147, v93
	ds_read_b64_tr_b16 v[146:147], v112
	v_add_u32_e32 v112, v148, v93
	ds_read_b64_tr_b16 v[148:149], v112
	s_waitcnt lgkmcnt(0)
	v_mfma_f32_16x16x32_bf16 v[106:109], v[106:109], v[102:105], 0
	v_mfma_f32_16x16x32_bf16 v[122:125], v[122:125], v[102:105], 0
	v_mfma_f32_16x16x32_bf16 v[126:129], v[126:129], v[102:105], 0
	v_mfma_f32_16x16x32_bf16 v[130:133], v[130:133], v[102:105], 0
	v_add_f32_e32 v112, v150, v158
	v_add_f32_e32 v112, v151, v112
	v_mfma_f32_16x16x32_bf16 v[134:137], v[134:137], v[102:105], 0
	v_add_f32_e32 v112, v152, v112
	v_add_f32_e32 v112, v153, v112
	v_add_f32_e32 v112, v154, v112
	v_mfma_f32_16x16x32_bf16 v[138:141], v[138:141], v[102:105], 0
	v_add_f32_e32 v112, v155, v112
	v_bfe_u32 v160, v153, 16, 1
	v_mfma_f32_16x16x32_bf16 v[142:145], v[142:145], v[102:105], 0
	v_add_f32_e32 v112, v156, v112
	v_add_f32_e32 v112, v157, v112
	v_mfma_f32_16x16x32_bf16 v[102:105], v[146:149], v[102:105], 0
	v_add3_u32 v147, v153, v160, s78
	v_bfe_u32 v153, v152, 16, 1
	v_cvt_pk_bf16_f32 v146, v150, v151
	v_or3_b32 v150, s22, v83, v120
	v_add3_u32 v152, v152, v153, s78
	v_lshl_add_u32 v180, v150, 8, v86
	v_lshrrev_b32_e32 v151, 16, v152
	v_add3_u32 v181, v86, s51, v97
	v_add_u32_e32 v150, v180, v98
	v_cvt_pk_bf16_f32 v148, v154, v155
	v_and_or_b32 v147, v147, s79, v151
	ds_read_b64_tr_b16 v[150:151], v150
	v_add_u32_e32 v152, v181, v98
	v_cvt_pk_bf16_f32 v149, v156, v157
	ds_read_b64_tr_b16 v[152:153], v152
	v_add_u32_e32 v154, v180, v99
	ds_read_b64_tr_b16 v[154:155], v154
	v_add_u32_e32 v156, v181, v99
	ds_read_b64_tr_b16 v[156:157], v156
	v_add_u32_e32 v158, v180, v100
	ds_read_b64_tr_b16 v[158:159], v158
	v_add_u32_e32 v160, v181, v100
	ds_read_b64_tr_b16 v[160:161], v160
	v_add_u32_e32 v162, v180, v101
	ds_read_b64_tr_b16 v[162:163], v162
	v_add_u32_e32 v164, v181, v101
	ds_read_b64_tr_b16 v[164:165], v164
	s_waitcnt lgkmcnt(0)
	v_mfma_f32_16x16x32_bf16 v[106:109], v[150:153], v[146:149], v[106:109]
	v_add_u32_e32 v150, v180, v94
	ds_read_b64_tr_b16 v[150:151], v150
	v_add_u32_e32 v152, v181, v94
	v_mfma_f32_16x16x32_bf16 v[122:125], v[154:157], v[146:149], v[122:125]
	ds_read_b64_tr_b16 v[152:153], v152
	v_add_u32_e32 v154, v180, v95
	ds_read_b64_tr_b16 v[154:155], v154
	v_add_u32_e32 v156, v181, v95
	v_mfma_f32_16x16x32_bf16 v[126:129], v[158:161], v[146:149], v[126:129]
	ds_read_b64_tr_b16 v[156:157], v156
	v_add_u32_e32 v158, v180, v96
	ds_read_b64_tr_b16 v[158:159], v158
	v_add_u32_e32 v160, v181, v96
	v_mfma_f32_16x16x32_bf16 v[130:133], v[162:165], v[146:149], v[130:133]
	ds_read_b64_tr_b16 v[160:161], v160
	v_add_u32_e32 v162, v180, v93
	ds_read_b64_tr_b16 v[162:163], v162
	v_add_u32_e32 v164, v181, v93
	ds_read_b64_tr_b16 v[164:165], v164
	s_waitcnt lgkmcnt(0)
; __device__ __forceinline__ unsigned pk2(float lo, float hi) { return f2bf(lo) | (f2bf(hi) << 16); }
; __device__ __forceinline__ s16x4 tr_read_b64(unsigned addr) { s16x4 r; asm volatile("ds_read_b64_tr_b16 %0, %1" : "=v"(r) : "v"(addr) : "memory"); return r; }
; template <int L>
; __device__ __forceinline__ void layer_body(const Args& args, LAS unsigned char* lds, const int wave, const int G, const int gw, const int NGW, const int lo, const int hi,
;                                            unsigned char* const ws_kernel, const XcdBarrier& bar, int& pid) {
;     ...
;                         for (int j = 0; j < 4; ++j) { sc[t][j] = __builtin_amdgcn_exp2f(sc[t][j] - mx); sum += sc[t][j]; }
;                     sum += __shfl_xor(sum, 16); sum += __shfl_xor(sum, 32);
;                     f32x4 acc[8];
; #pragma unroll
;                     for (int mt = 0; mt < 8; ++mt) acc[mt] = (f32x4){0.f, 0.f, 0.f, 0.f};
;                     const int trq = (lane & 15) >> 2, trp = lane & 3;
; #pragma unroll
;                     for (int s = 0; s < 5; ++s) {
;                         const int T0 = min(wave + 2 * s, 15), T1 = min(wave + 2 * s + 1, 15);
;                         bf16x8 pb; { const f32x4 p0 = sc[2 * s], p1 = sc[2 * s + 1]; v4u w; w.x = pk2(p0[0], p0[1]); w.y = pk2(p0[2], p0[3]); w.z = pk2(p1[0], p1[1]); w.w = pk2(p1[2], p1[3]); pb = __builtin_bit_cast(bf16x8, w); }
; #pragma unroll
;                         for (int mh = 0; mh < 2; ++mh) {
;                             s16x4 lo[4], hi[4];
; #pragma unroll
;                             for (int m4 = 0; m4 < 4; ++m4) { const int mt = mh * 4 + m4, r0_ = 16 * T0 + 4 * kg + trq, r1_ = 16 * T1 + 4 * kg + trq, ch_ = 2 * mt + (trp >> 1);
;                                 lo[m4] = tr_read_b64(Vimg + vimg_off(r0_, ch_) + 8u * (trp & 1)); hi[m4] = tr_read_b64(Vimg + vimg_off(r1_, ch_) + 8u * (trp & 1)); }
;                             asm volatile("s_waitcnt lgkmcnt(0)" ::: "memory"); __builtin_amdgcn_sched_barrier(0);
; #pragma unroll
;                             for (int m4 = 0; m4 < 4; ++m4) { const int mt = mh * 4 + m4; const bf16x8 va = (bf16x8){lo[m4][0], lo[m4][1], lo[m4][2], lo[m4][3], hi[m4][0], hi[m4][1], hi[m4][2], hi[m4][3]};
;                                 acc[mt] = __builtin_amdgcn_mfma_f32_16x16x32_bf16(va, pb, acc[mt], 0, 0, 0); }
	v_add_f32_e32 v112, v166, v112
	v_add_f32_e32 v112, v167, v112
	v_mfma_f32_16x16x32_bf16 v[134:137], v[150:153], v[146:149], v[134:137]
	v_add_f32_e32 v112, v110, v112
	v_add_f32_e32 v112, v111, v112
	v_mfma_f32_16x16x32_bf16 v[138:141], v[154:157], v[146:149], v[138:141]
	v_mfma_f32_16x16x32_bf16 v[142:145], v[158:161], v[146:149], v[142:145]
	v_add_f32_e32 v112, v168, v112
	v_add_f32_e32 v112, v169, v112
	v_add_f32_e32 v112, v170, v112
	v_mfma_f32_16x16x32_bf16 v[102:105], v[162:165], v[146:149], v[102:105]
	v_bfe_u32 v149, v166, 16, 1
	v_add3_u32 v149, v166, v149, s78
	v_lshrrev_b32_e32 v150, 16, v149
	v_bfe_u32 v146, v167, 16, 1
	v_cvt_pk_bf16_f32 v149, v170, v171
	v_cvt_pk_bf16_f32 v148, v168, v169
	v_cvt_pk_bf16_f32 v147, v110, v111
	v_or3_b32 v110, s38, v83, v120
	v_add3_u32 v146, v167, v146, s78
	v_lshl_add_u32 v110, v110, 8, v86
	v_and_or_b32 v146, v146, s79, v150
	v_add3_u32 v111, v86, s52, v97
	v_add_u32_e32 v150, v110, v98
	ds_read_b64_tr_b16 v[150:151], v150
	v_add_u32_e32 v152, v111, v98
	ds_read_b64_tr_b16 v[152:153], v152
	v_add_u32_e32 v154, v110, v99
	ds_read_b64_tr_b16 v[154:155], v154
	v_add_u32_e32 v156, v111, v99
	ds_read_b64_tr_b16 v[156:157], v156
	v_add_u32_e32 v158, v110, v100
	ds_read_b64_tr_b16 v[158:159], v158
	v_add_u32_e32 v160, v111, v100
	ds_read_b64_tr_b16 v[160:161], v160
	v_add_u32_e32 v162, v110, v101
	ds_read_b64_tr_b16 v[162:163], v162
	v_add_u32_e32 v164, v111, v101
	ds_read_b64_tr_b16 v[164:165], v164
	s_waitcnt lgkmcnt(0)
	v_add_f32_e32 v112, v171, v112
	v_mfma_f32_16x16x32_bf16 v[106:109], v[150:153], v[146:149], v[106:109]
	v_add_u32_e32 v150, v110, v94
	ds_read_b64_tr_b16 v[150:151], v150
	v_add_u32_e32 v152, v111, v94
	v_mfma_f32_16x16x32_bf16 v[122:125], v[154:157], v[146:149], v[122:125]
	ds_read_b64_tr_b16 v[152:153], v152
	v_add_u32_e32 v154, v110, v95
	ds_read_b64_tr_b16 v[154:155], v154
	v_add_u32_e32 v156, v111, v95
	v_mfma_f32_16x16x32_bf16 v[126:129], v[158:161], v[146:149], v[126:129]
	ds_read_b64_tr_b16 v[156:157], v156
	v_add_u32_e32 v158, v110, v96
	ds_read_b64_tr_b16 v[158:159], v158
	v_add_u32_e32 v160, v111, v96
	ds_read_b64_tr_b16 v[160:161], v160
	v_mfma_f32_16x16x32_bf16 v[130:133], v[162:165], v[146:149], v[130:133]
	v_add_u32_e32 v110, v110, v93
	ds_read_b64_tr_b16 v[162:163], v110
	v_add_u32_e32 v110, v111, v93
	ds_read_b64_tr_b16 v[164:165], v110
	s_waitcnt lgkmcnt(0)
	v_mfma_f32_16x16x32_bf16 v[134:137], v[150:153], v[146:149], v[134:137]
	v_bfe_u32 v150, v175, 16, 1
	v_mfma_f32_16x16x32_bf16 v[138:141], v[154:157], v[146:149], v[138:141]
	v_add_f32_e32 v110, v172, v112
	v_mfma_f32_16x16x32_bf16 v[142:145], v[158:161], v[146:149], v[142:145]
	v_add_f32_e32 v110, v173, v110
	v_mfma_f32_16x16x32_bf16 v[102:105], v[162:165], v[146:149], v[102:105]
	v_bfe_u32 v149, v174, 16, 1
	v_add3_u32 v149, v174, v149, s78
	v_add3_u32 v147, v175, v150, s78
	v_bfe_u32 v148, v172, 16, 1
	v_lshrrev_b32_e32 v153, 16, v149
	v_add3_u32 v148, v172, v148, s78
	v_cvt_pk_bf16_f32 v149, v178, v179
	v_or3_b32 v111, s42, v83, v120
	v_bfe_u32 v146, v173, 16, 1
	v_lshrrev_b32_e32 v152, 16, v148
	v_lshl_add_u32 v111, v111, 8, v86
	v_add3_u32 v146, v173, v146, s78
	v_cvt_pk_bf16_f32 v148, v176, v177
	v_add3_u32 v112, v86, s53, v97
	v_add_u32_e32 v150, v111, v98
	v_and_or_b32 v146, v146, s79, v152
	ds_read_b64_tr_b16 v[150:151], v150
	v_add_u32_e32 v152, v112, v98
	v_and_or_b32 v147, v147, s79, v153
	ds_read_b64_tr_b16 v[152:153], v152
	v_add_u32_e32 v154, v111, v99
	ds_read_b64_tr_b16 v[154:155], v154
	v_add_u32_e32 v156, v112, v99
	ds_read_b64_tr_b16 v[156:157], v156
	v_add_u32_e32 v158, v111, v100
	ds_read_b64_tr_b16 v[158:159], v158
	v_add_u32_e32 v160, v112, v100
	ds_read_b64_tr_b16 v[160:161], v160
	v_add_u32_e32 v162, v111, v101
	v_add_f32_e32 v110, v174, v110
	ds_read_b64_tr_b16 v[162:163], v162
	v_add_u32_e32 v164, v112, v101
	v_add_f32_e32 v110, v175, v110
	ds_read_b64_tr_b16 v[164:165], v164
	v_add_f32_e32 v110, v176, v110
	s_waitcnt lgkmcnt(0)
	v_add_f32_e32 v110, v177, v110
	v_add_f32_e32 v110, v178, v110
	v_add_f32_e32 v110, v179, v110
	v_mfma_f32_16x16x32_bf16 v[106:109], v[150:153], v[146:149], v[106:109]
	v_add_u32_e32 v150, v111, v94
	ds_read_b64_tr_b16 v[150:151], v150
	v_add_u32_e32 v152, v112, v94
	v_mfma_f32_16x16x32_bf16 v[122:125], v[154:157], v[146:149], v[122:125]
	ds_read_b64_tr_b16 v[152:153], v152
	v_add_u32_e32 v154, v111, v95
	ds_read_b64_tr_b16 v[154:155], v154
	v_add_u32_e32 v156, v112, v95
	v_mfma_f32_16x16x32_bf16 v[126:129], v[158:161], v[146:149], v[126:129]
	ds_read_b64_tr_b16 v[156:157], v156
	v_add_u32_e32 v158, v111, v96
	ds_read_b64_tr_b16 v[158:159], v158
	v_add_u32_e32 v160, v112, v96
	ds_read_b64_tr_b16 v[160:161], v160
	v_mfma_f32_16x16x32_bf16 v[130:133], v[162:165], v[146:149], v[130:133]
	v_add_u32_e32 v111, v111, v93
	ds_read_b64_tr_b16 v[162:163], v111
	v_add_u32_e32 v111, v112, v93
	ds_read_b64_tr_b16 v[164:165], v111
	s_waitcnt lgkmcnt(0)
	v_add_f32_e32 v110, v81, v110
	v_add_f32_e32 v110, v88, v110
	v_add_f32_e32 v110, v85, v110
	v_add_f32_e32 v110, v90, v110
	v_add_f32_e32 v110, v87, v110
	v_add_f32_e32 v110, v91, v110
	v_add_f32_e32 v110, v89, v110
	v_add_f32_e32 v110, v92, v110
	ds_bpermute_b32 v80, v80, v110
	v_bfe_u32 v111, v91, 16, 1
	v_bfe_u32 v112, v90, 16, 1
	v_add3_u32 v112, v90, v112, s78
	v_add3_u32 v90, v91, v111, s78
	v_mfma_f32_16x16x32_bf16 v[134:137], v[150:153], v[146:149], v[134:137]
	s_waitcnt lgkmcnt(0)
; __device__ __forceinline__ unsigned pk2(float lo, float hi) { return f2bf(lo) | (f2bf(hi) << 16); }
; __device__ __forceinline__ s16x4 tr_read_b64(unsigned addr) { s16x4 r; asm volatile("ds_read_b64_tr_b16 %0, %1" : "=v"(r) : "v"(addr) : "memory"); return r; }
; template <int L>
; __device__ __forceinline__ void layer_body(const Args& args, LAS unsigned char* lds, const int wave, const int G, const int gw, const int NGW, const int lo, const int hi,
;                                            unsigned char* const ws_kernel, const XcdBarrier& bar, int& pid) {
;     ...
;                     sum += __shfl_xor(sum, 16); sum += __shfl_xor(sum, 32);
;     ...
;                     for (int s = 0; s < 5; ++s) {
;                         const int T0 = min(wave + 2 * s, 15), T1 = min(wave + 2 * s + 1, 15);
;                         bf16x8 pb; { const f32x4 p0 = sc[2 * s], p1 = sc[2 * s + 1]; v4u w; w.x = pk2(p0[0], p0[1]); w.y = pk2(p0[2], p0[3]); w.z = pk2(p1[0], p1[1]); w.w = pk2(p1[2], p1[3]); pb = __builtin_bit_cast(bf16x8, w); }
; #pragma unroll
;                         for (int mh = 0; mh < 2; ++mh) {
;                             s16x4 lo[4], hi[4];
; #pragma unroll
;                             for (int m4 = 0; m4 < 4; ++m4) { const int mt = mh * 4 + m4, r0_ = 16 * T0 + 4 * kg + trq, r1_ = 16 * T1 + 4 * kg + trq, ch_ = 2 * mt + (trp >> 1);
;                                 lo[m4] = tr_read_b64(Vimg + vimg_off(r0_, ch_) + 8u * (trp & 1)); hi[m4] = tr_read_b64(Vimg + vimg_off(r1_, ch_) + 8u * (trp & 1)); }
;                             asm volatile("s_waitcnt lgkmcnt(0)" ::: "memory"); __builtin_amdgcn_sched_barrier(0);
; #pragma unroll
;                             for (int m4 = 0; m4 < 4; ++m4) { const int mt = mh * 4 + m4; const bf16x8 va = (bf16x8){lo[m4][0], lo[m4][1], lo[m4][2], lo[m4][3], hi[m4][0], hi[m4][1], hi[m4][2], hi[m4][3]};
;                                 acc[mt] = __builtin_amdgcn_mfma_f32_16x16x32_bf16(va, pb, acc[mt], 0, 0, 0); }
	v_add_f32_e32 v80, v110, v80
	ds_bpermute_b32 v110, v84, v80
	v_mfma_f32_16x16x32_bf16 v[138:141], v[154:157], v[146:149], v[138:141]
	v_bfe_u32 v84, v92, 16, 1
	v_add3_u32 v84, v92, v84, s78
	v_mfma_f32_16x16x32_bf16 v[142:145], v[158:161], v[146:149], v[142:145]
	v_bfe_u32 v92, v85, 16, 1
	v_bfe_u32 v111, v87, 16, 1
	v_add3_u32 v85, v85, v92, s78
	v_mfma_f32_16x16x32_bf16 v[102:105], v[162:165], v[146:149], v[102:105]
	v_bfe_u32 v146, v89, 16, 1
	v_add3_u32 v89, v89, v146, s78
	v_cvt_pk_bf16_f32 v88, v81, v88
	v_or3_b32 v81, s46, v83, v120
	v_lshrrev_b32_e32 v89, 16, v89
	v_lshl_add_u32 v81, v81, 8, v86
	v_add3_u32 v87, v87, v111, s78
	v_lshrrev_b32_e32 v85, 16, v85
	v_and_or_b32 v91, v84, s79, v89
	v_add3_u32 v83, v86, s54, v97
	v_add_u32_e32 v84, v81, v98
	v_lshrrev_b32_e32 v87, 16, v87
	v_and_or_b32 v89, v112, s79, v85
	ds_read_b64_tr_b16 v[84:85], v84
	v_add_u32_e32 v86, v83, v98
	v_and_or_b32 v90, v90, s79, v87
	ds_read_b64_tr_b16 v[86:87], v86
	v_add_u32_e32 v92, v81, v99
	ds_read_b64_tr_b16 v[146:147], v92
	v_add_u32_e32 v92, v83, v99
	ds_read_b64_tr_b16 v[148:149], v92
	v_add_u32_e32 v92, v81, v100
	ds_read_b64_tr_b16 v[150:151], v92
	v_add_u32_e32 v92, v83, v100
	ds_read_b64_tr_b16 v[152:153], v92
	v_add_u32_e32 v92, v81, v101
	ds_read_b64_tr_b16 v[98:99], v92
	v_add_u32_e32 v92, v83, v101
	ds_read_b64_tr_b16 v[100:101], v92
	s_waitcnt lgkmcnt(0)
	v_mfma_f32_16x16x32_bf16 v[84:87], v[84:87], v[88:91], v[106:109]
	v_add_u32_e32 v92, v81, v94
	v_mfma_f32_16x16x32_bf16 v[106:109], v[146:149], v[88:91], v[122:125]
	v_mfma_f32_16x16x32_bf16 v[122:125], v[150:153], v[88:91], v[126:129]
	ds_read_b64_tr_b16 v[126:127], v92
	v_add_u32_e32 v92, v83, v94
	ds_read_b64_tr_b16 v[128:129], v92
	v_mfma_f32_16x16x32_bf16 v[98:101], v[98:101], v[88:91], v[130:133]
	v_add_u32_e32 v92, v81, v95
	ds_read_b64_tr_b16 v[130:131], v92
	v_add_u32_e32 v92, v83, v95
	ds_read_b64_tr_b16 v[132:133], v92
	v_add_u32_e32 v92, v81, v96
	ds_read_b64_tr_b16 v[94:95], v92
	v_add_u32_e32 v92, v83, v96
	ds_read_b64_tr_b16 v[96:97], v92
	v_add_u32_e32 v81, v81, v93
	ds_read_b64_tr_b16 v[146:147], v81
	v_add_u32_e32 v81, v83, v93
	ds_read_b64_tr_b16 v[148:149], v81
	s_waitcnt lgkmcnt(0)
	s_waitcnt lgkmcnt(0)
; #define GAS __attribute__((address_space(1)))
; __device__ __forceinline__ unsigned pk2(float lo, float hi) { return f2bf(lo) | (f2bf(hi) << 16); }
; template <int L>
; __device__ __forceinline__ void layer_body(const Args& args, LAS unsigned char* lds, const int wave, const int G, const int gw, const int NGW, const int lo, const int hi,
;                                            unsigned char* const ws_kernel, const XcdBarrier& bar, int& pid) {
;     ...
;                             for (int m4 = 0; m4 < 4; ++m4) { const int mt = mh * 4 + m4; const bf16x8 va = (bf16x8){lo[m4][0], lo[m4][1], lo[m4][2], lo[m4][3], hi[m4][0], hi[m4][1], hi[m4][2], hi[m4][3]};
;                                 acc[mt] = __builtin_amdgcn_mfma_f32_16x16x32_bf16(va, pb, acc[mt], 0, 0, 0); }
;                         }
;                     }
;                     const float inv = 1.0f / sum; const int tq = b * SEQ + mq * dil + rho;
;                     GAS bf16* op = (GAS bf16*)(opart + ((size_t)g * (M / 2) + tq) * D + h * HD + 4 * kg);
; #pragma unroll
;                     for (int mt = 0; mt < 8; ++mt) { v2u w; w.x = pk2(acc[mt][0] * inv, acc[mt][1] * inv); w.y = pk2(acc[mt][2] * inv, acc[mt][3] * inv); *(GAS v2u*)(op + 16 * mt) = w; }
;                     if (kg == 0) ((GAS float*)lsebuf)[((size_t)g * (M / 2) + tq) * NH + h] = mx + __log2f(sum);
	v_add_f32_e32 v83, v80, v110
	v_div_scale_f32 v80, s[68:69], v83, v83, 1.0
	v_rcp_f32_e32 v81, v80
	v_div_scale_f32 v110, vcc, 1.0, v83, 1.0
	s_lshl_b32 s3, s12, 7
	v_fma_f32 v92, -v80, v81, 1.0
	v_fmac_f32_e32 v81, v92, v81
	v_mfma_f32_16x16x32_bf16 v[92:95], v[94:97], v[88:91], v[142:145]
	v_mul_f32_e32 v96, v110, v81
	v_fma_f32 v97, -v80, v96, v110
	v_fmac_f32_e32 v96, v97, v81
	v_fma_f32 v80, -v80, v96, v110
	v_div_fmas_f32 v80, v80, v81, v96
	s_and_b32 s3, s3, 0xfffff800
	v_div_fixup_f32 v96, v80, v83, 1.0
	v_lshlrev_b32_e32 v80, s67, v121
	s_or_b32 s2, s2, s3
	v_mfma_f32_16x16x32_bf16 v[126:129], v[126:129], v[88:91], v[134:137]
	v_add_u32_e32 v80, s2, v80
	s_ashr_i32 s67, s66, 31
	s_lshl_b64 s[2:3], s[66:67], 12
	v_mfma_f32_16x16x32_bf16 v[130:133], v[130:133], v[88:91], v[138:141]
	v_ashrrev_i32_e32 v81, 31, v80
	v_lshl_add_u64 v[80:81], s[2:3], 0, v[80:81]
	s_lshl_b32 s12, s4, 8
	v_mfma_f32_16x16x32_bf16 v[88:91], v[146:149], v[88:91], v[102:105]
	v_lshlrev_b32_e32 v112, 1, v120
	v_cmp_eq_u32_e32 vcc, 0, v119
	s_nop 0
	v_mov_b32_e32 v104, v84
	v_mov_b32_e32 v105, v86
	v_pk_mul_f32 v[104:105], v[96:97], v[104:105] op_sel_hi:[0,1]
	v_mov_b32_e32 v86, v85
	v_pk_mul_f32 v[84:85], v[96:97], v[86:87] op_sel_hi:[0,1]
	v_lshlrev_b64 v[102:103], 12, v[80:81]
	v_and_b32_sdwa v97, v85, v118 dst_sel:DWORD dst_unused:UNUSED_PAD src0_sel:WORD_1 src1_sel:DWORD
	v_lshl_add_u64 v[102:103], s[60:61], 0, v[102:103]
	v_and_b32_sdwa v86, v105, v118 dst_sel:DWORD dst_unused:UNUSED_PAD src0_sel:WORD_1 src1_sel:DWORD
	v_add3_u32 v85, v85, v97, s78
	v_lshl_add_u64 v[102:103], v[102:103], 0, s[12:13]
	v_add3_u32 v86, v105, v86, s78
	v_and_b32_e32 v85, 0xffff0000, v85
	v_lshl_add_u64 v[102:103], v[102:103], 0, v[112:113]
	v_or_b32_sdwa v85, v85, v86 dst_sel:DWORD dst_unused:UNUSED_PAD src0_sel:DWORD src1_sel:WORD_1
	v_cvt_pk_bf16_f32 v84, v104, v84
	global_store_dwordx2 v[102:103], v[84:85], off
	v_mov_b32_e32 v84, v106
	v_mov_b32_e32 v85, v108
	v_pk_mul_f32 v[84:85], v[96:97], v[84:85] op_sel_hi:[0,1]
	v_mov_b32_e32 v108, v107
	v_pk_mul_f32 v[86:87], v[96:97], v[108:109] op_sel_hi:[0,1]
	v_and_b32_sdwa v97, v85, v118 dst_sel:DWORD dst_unused:UNUSED_PAD src0_sel:WORD_1 src1_sel:DWORD
	v_add3_u32 v85, v85, v97, s78
	v_and_b32_sdwa v97, v87, v118 dst_sel:DWORD dst_unused:UNUSED_PAD src0_sel:WORD_1 src1_sel:DWORD
	v_add3_u32 v87, v87, v97, s78
	v_and_b32_e32 v87, 0xffff0000, v87
	v_or_b32_sdwa v85, v87, v85 dst_sel:DWORD dst_unused:UNUSED_PAD src0_sel:DWORD src1_sel:WORD_1
	v_cvt_pk_bf16_f32 v84, v84, v86
	global_store_dwordx2 v[102:103], v[84:85], off offset:32
	v_mov_b32_e32 v84, v122
	v_mov_b32_e32 v85, v124
	v_pk_mul_f32 v[84:85], v[96:97], v[84:85] op_sel_hi:[0,1]
	v_mov_b32_e32 v124, v123
	v_pk_mul_f32 v[86:87], v[96:97], v[124:125] op_sel_hi:[0,1]
	v_and_b32_sdwa v97, v85, v118 dst_sel:DWORD dst_unused:UNUSED_PAD src0_sel:WORD_1 src1_sel:DWORD
	v_add3_u32 v85, v85, v97, s78
	v_and_b32_sdwa v97, v87, v118 dst_sel:DWORD dst_unused:UNUSED_PAD src0_sel:WORD_1 src1_sel:DWORD
	v_add3_u32 v87, v87, v97, s78
	v_and_b32_e32 v87, 0xffff0000, v87
	v_or_b32_sdwa v85, v87, v85 dst_sel:DWORD dst_unused:UNUSED_PAD src0_sel:DWORD src1_sel:WORD_1
	v_cvt_pk_bf16_f32 v84, v84, v86
	global_store_dwordx2 v[102:103], v[84:85], off offset:64
	v_mov_b32_e32 v84, v98
	v_mov_b32_e32 v85, v100
	v_pk_mul_f32 v[84:85], v[96:97], v[84:85] op_sel_hi:[0,1]
	v_mov_b32_e32 v100, v99
	v_pk_mul_f32 v[86:87], v[96:97], v[100:101] op_sel_hi:[0,1]
	v_and_b32_sdwa v97, v85, v118 dst_sel:DWORD dst_unused:UNUSED_PAD src0_sel:WORD_1 src1_sel:DWORD
	v_add3_u32 v85, v85, v97, s78
	v_and_b32_sdwa v97, v87, v118 dst_sel:DWORD dst_unused:UNUSED_PAD src0_sel:WORD_1 src1_sel:DWORD
	v_add3_u32 v87, v87, v97, s78
	v_and_b32_e32 v87, 0xffff0000, v87
	v_or_b32_sdwa v85, v87, v85 dst_sel:DWORD dst_unused:UNUSED_PAD src0_sel:DWORD src1_sel:WORD_1
	v_cvt_pk_bf16_f32 v84, v84, v86
	global_store_dwordx2 v[102:103], v[84:85], off offset:96
	v_mov_b32_e32 v84, v126
	v_mov_b32_e32 v85, v128
	v_pk_mul_f32 v[84:85], v[96:97], v[84:85] op_sel_hi:[0,1]
	v_mov_b32_e32 v128, v127
	v_pk_mul_f32 v[86:87], v[96:97], v[128:129] op_sel_hi:[0,1]
	v_and_b32_sdwa v97, v85, v118 dst_sel:DWORD dst_unused:UNUSED_PAD src0_sel:WORD_1 src1_sel:DWORD
	v_add3_u32 v85, v85, v97, s78
	v_and_b32_sdwa v97, v87, v118 dst_sel:DWORD dst_unused:UNUSED_PAD src0_sel:WORD_1 src1_sel:DWORD
	v_add3_u32 v87, v87, v97, s78
	v_and_b32_e32 v87, 0xffff0000, v87
	v_or_b32_sdwa v85, v87, v85 dst_sel:DWORD dst_unused:UNUSED_PAD src0_sel:DWORD src1_sel:WORD_1
	v_cvt_pk_bf16_f32 v84, v84, v86
	global_store_dwordx2 v[102:103], v[84:85], off offset:128
	v_mov_b32_e32 v84, v130
	v_mov_b32_e32 v85, v132
	v_pk_mul_f32 v[84:85], v[96:97], v[84:85] op_sel_hi:[0,1]
	v_mov_b32_e32 v132, v131
	v_pk_mul_f32 v[86:87], v[96:97], v[132:133] op_sel_hi:[0,1]
	v_and_b32_sdwa v97, v85, v118 dst_sel:DWORD dst_unused:UNUSED_PAD src0_sel:WORD_1 src1_sel:DWORD
	v_add3_u32 v85, v85, v97, s78
	v_and_b32_sdwa v97, v87, v118 dst_sel:DWORD dst_unused:UNUSED_PAD src0_sel:WORD_1 src1_sel:DWORD
	v_add3_u32 v87, v87, v97, s78
	v_and_b32_e32 v87, 0xffff0000, v87
	v_or_b32_sdwa v85, v87, v85 dst_sel:DWORD dst_unused:UNUSED_PAD src0_sel:DWORD src1_sel:WORD_1
	v_cvt_pk_bf16_f32 v84, v84, v86
	global_store_dwordx2 v[102:103], v[84:85], off offset:160
	v_mov_b32_e32 v84, v92
	v_mov_b32_e32 v85, v94
	v_pk_mul_f32 v[84:85], v[96:97], v[84:85] op_sel_hi:[0,1]
	v_mov_b32_e32 v94, v93
	v_pk_mul_f32 v[86:87], v[96:97], v[94:95] op_sel_hi:[0,1]
	v_cvt_pk_bf16_f32 v85, v85, v87
	v_cvt_pk_bf16_f32 v84, v84, v86
	global_store_dwordx2 v[102:103], v[84:85], off offset:192
	v_mov_b32_e32 v84, v88
	v_mov_b32_e32 v85, v90
	v_pk_mul_f32 v[84:85], v[96:97], v[84:85] op_sel_hi:[0,1]
	v_mov_b32_e32 v90, v89
	v_pk_mul_f32 v[86:87], v[96:97], v[90:91] op_sel_hi:[0,1]
	v_cvt_pk_bf16_f32 v85, v85, v87
	v_cvt_pk_bf16_f32 v84, v84, v86
	global_store_dwordx2 v[102:103], v[84:85], off offset:224
	s_and_saveexec_b64 s[2:3], vcc
	s_cbranch_execz .LBB0_1685
	v_log_f32_e32 v83, v83
	v_lshlrev_b64 v[80:81], 6, v[80:81]
	v_lshl_add_u64 v[80:81], s[62:63], 0, v[80:81]
	s_lshl_b32 s12, s4, 2
	v_add_f32_e32 v82, v82, v83
	v_lshl_add_u64 v[80:81], v[80:81], 0, s[12:13]
	global_store_dword v[80:81], v82, off
	s_branch .LBB0_1685

; #define LAS __attribute__((address_space(3)))
; __device__ __forceinline__ unsigned pk2(float lo, float hi) { return f2bf(lo) | (f2bf(hi) << 16); }
; template <int L>
; __device__ __forceinline__ void layer_body(const Args& args, LAS unsigned char* lds, const int wave, const int G, const int gw, const int NGW, const int lo, const int hi,
;                                            unsigned char* const ws_kernel, const XcdBarrier& bar, int& pid) {
;     ...
;                     for (int s = 0; s < 8; ++s) { const f32x4 p0 = sc[2 * s], p1 = sc[2 * s + 1]; v4u w; w.x = pk2(p0[0], p0[1]); w.y = pk2(p0[2], p0[3]); w.z = pk2(p1[0], p1[1]); w.w = pk2(p1[2], p1[3]); pbf[s] = __builtin_bit_cast(bf16x8, w); }
;                     __syncthreads();
; #pragma unroll
;                     for (int i = 0; i < 14; ++i) { const int kid = skey + 32 * i; *(LAS v4u*)(size_t)(IMG + vimg_off(kid, sch)) = rst[i]; }
;                     __syncthreads();
;                     if (unit + GH < UEND) { NA_LOADROWS(unit + GH, rst, D); NA_LOADQ(unit + GH); }
;                     f32x4 acc[8];
; #pragma unroll
;                     for (int mt = 0; mt < 8; ++mt) acc[mt] = (f32x4){0.f, 0.f, 0.f, 0.f};
;                     const int trq = (lane & 15) >> 2, trp = lane & 3;
; #pragma unroll
;                     for (int s = 0; s < 8; ++s) {
;                         const int ir0 = (r0w - krlo + s) * 40 + coloff;
; #pragma unroll
;                         for (int mh = 0; mh < 2; ++mh) {
;                             s16x4 lo[4], hi[4];
; #pragma unroll
;                             for (int m4 = 0; m4 < 4; ++m4) { const int mt = mh * 4 + m4, r0_ = ir0 + 4 * kg + trq, r1_ = ir0 + 16 + 4 * kg + trq, ch_ = 2 * mt + (trp >> 1);
;                                 lo[m4] = tr_read_b64(IMG + vimg_off(r0_, ch_) + 8u * (trp & 1)); hi[m4] = tr_read_b64(IMG + vimg_off(r1_, ch_) + 8u * (trp & 1)); }
;                             asm volatile("s_waitcnt lgkmcnt(0)" ::: "memory"); __builtin_amdgcn_sched_barrier(0);
; #pragma unroll
;                             for (int m4 = 0; m4 < 4; ++m4) { const int mt = mh * 4 + m4; const bf16x8 va = (bf16x8){lo[m4][0], lo[m4][1], lo[m4][2], lo[m4][3], hi[m4][0], hi[m4][1], hi[m4][2], hi[m4][3]};
;                                 acc[mt] = __builtin_amdgcn_mfma_f32_16x16x32_bf16(va, pbf[s], acc[mt], 0, 0, 0); }
.LBB0_3408:
	v_cvt_pk_bf16_f32 v101, v194, v200
	v_cvt_pk_bf16_f32 v100, v190, v198
	v_cvt_pk_bf16_f32 v103, v199, v202
	v_cvt_pk_bf16_f32 v102, v196, v201
	v_cvt_pk_bf16_f32 v97, v186, v193
	v_cvt_pk_bf16_f32 v96, v180, v191
	v_cvt_pk_bf16_f32 v99, v192, v197
	v_cvt_pk_bf16_f32 v98, v188, v195
	v_cvt_pk_bf16_f32 v93, v178, v185
	v_cvt_pk_bf16_f32 v92, v177, v182
	v_cvt_pk_bf16_f32 v95, v184, v189
	v_cvt_pk_bf16_f32 v94, v179, v187
	v_cvt_pk_bf16_f32 v89, v142, v148
	v_cvt_pk_bf16_f32 v88, v138, v146
	v_cvt_pk_bf16_f32 v91, v147, v152
	v_cvt_pk_bf16_f32 v90, v144, v150
	v_cvt_pk_bf16_f32 v85, v134, v141
	v_cvt_pk_bf16_f32 v84, v130, v139
	v_cvt_pk_bf16_f32 v87, v140, v145
	v_cvt_pk_bf16_f32 v86, v136, v143
	v_cvt_pk_bf16_f32 v81, v126, v133
	v_cvt_pk_bf16_f32 v80, v122, v131
	v_bfe_u32 v78, v125, 16, 1
	v_add3_u32 v113, v125, v78, s64
	v_bfe_u32 v79, v118, 16, 1
	v_cvt_pk_bf16_f32 v83, v132, v137
	v_add3_u32 v79, v118, v79, s64
	v_cvt_pk_bf16_f32 v82, v128, v135
	v_lshrrev_b32_e32 v118, 16, v79
	v_cvt_pk_bf16_f32 v79, v124, v129
	v_cvt_pk_bf16_f32 v76, v75, v123
	v_cvt_pk_bf16_f32 v78, v120, v127
	v_and_or_b32 v77, v113, s65, v118
	v_bfe_u32 v114, v115, 16, 1
	v_add3_u32 v114, v115, v114, s64
	v_bfe_u32 v115, v72, 16, 1
	v_add3_u32 v72, v72, v115, s64
	v_lshrrev_b32_e32 v112, 2, v112
	v_lshrrev_b32_e32 v72, 16, v72
	v_cvt_pk_bf16_f32 v75, v116, v121
	v_or_b32_e32 v115, v109, v112
	s_add_i32 s68, s68, s67
	v_cvt_pk_bf16_f32 v73, v73, v117
	v_and_or_b32 v72, v114, s65, v72
	v_or_b32_e32 v113, 16, v115
	v_bfe_u32 v112, v111, 1, 1
	v_lshlrev_b32_e32 v111, 3, v111
	v_add_u32_e32 v114, s68, v115
	v_and_or_b32 v111, v111, 8, 0
	v_add_u32_e32 v116, s68, v113
	v_lshlrev_b32_e32 v117, 2, v114
	v_and_b32_e32 v152, 12, v117
	v_bfe_u32 v153, v114, 2, 2
	v_lshl_add_u32 v154, v114, 8, v111
	v_lshlrev_b32_e32 v114, 2, v116
	v_and_b32_e32 v155, 12, v114
	v_bitop3_b32 v114, v152, v112, v153 bitop3:0x36
	v_bfe_u32 v156, v116, 2, 2
	v_lshl_add_u32 v114, v114, 4, v154
	v_lshl_add_u32 v157, v116, 8, v111
	ds_read_b64_tr_b16 v[120:121], v114
	v_bitop3_b32 v114, v155, v112, v156 bitop3:0x36
	v_lshl_add_u32 v114, v114, 4, v157
	ds_read_b64_tr_b16 v[122:123], v114
	v_or_b32_e32 v114, 2, v112
	v_bitop3_b32 v116, v152, v114, v153 bitop3:0x36
	v_lshl_add_u32 v116, v116, 4, v154
	ds_read_b64_tr_b16 v[124:125], v116
	v_bitop3_b32 v116, v155, v114, v156 bitop3:0x36
	v_lshl_add_u32 v116, v116, 4, v157
	ds_read_b64_tr_b16 v[126:127], v116
	v_or_b32_e32 v116, 4, v112
	v_bitop3_b32 v117, v152, v116, v153 bitop3:0x36
	v_lshl_add_u32 v117, v117, 4, v154
	ds_read_b64_tr_b16 v[128:129], v117
	v_bitop3_b32 v117, v155, v116, v156 bitop3:0x36
	v_lshl_add_u32 v117, v117, 4, v157
	ds_read_b64_tr_b16 v[130:131], v117
	v_or_b32_e32 v117, 6, v112
	v_bitop3_b32 v118, v152, v117, v153 bitop3:0x36
	v_lshl_add_u32 v118, v118, 4, v154
	ds_read_b64_tr_b16 v[132:133], v118
	v_bitop3_b32 v118, v155, v117, v156 bitop3:0x36
	v_lshl_add_u32 v118, v118, 4, v157
	ds_read_b64_tr_b16 v[134:135], v118
	s_waitcnt lgkmcnt(0)
	v_cvt_pk_bf16_f32 v74, v74, v119
	v_add_f32_e32 v104, v149, v151
	v_or_b32_e32 v118, 8, v112
	v_bitop3_b32 v119, v152, v118, v153 bitop3:0x36
	v_lshl_add_u32 v119, v119, 4, v154
	v_mfma_f32_16x16x32_bf16 v[136:139], v[120:123], v[100:103], 0
	ds_read_b64_tr_b16 v[122:123], v119
	v_bitop3_b32 v119, v155, v118, v156 bitop3:0x36
	v_lshl_add_u32 v119, v119, 4, v157
	v_mfma_f32_16x16x32_bf16 v[140:143], v[124:127], v[100:103], 0
	ds_read_b64_tr_b16 v[124:125], v119
	v_or_b32_e32 v119, 10, v112
	v_bitop3_b32 v120, v152, v119, v153 bitop3:0x36
	v_lshl_add_u32 v120, v120, 4, v154
	v_mfma_f32_16x16x32_bf16 v[126:129], v[128:131], v[100:103], 0
	ds_read_b64_tr_b16 v[130:131], v120
	v_bitop3_b32 v120, v155, v119, v156 bitop3:0x36
	v_lshl_add_u32 v120, v120, 4, v157
	v_mfma_f32_16x16x32_bf16 v[144:147], v[132:135], v[100:103], 0
	ds_read_b64_tr_b16 v[132:133], v120
	v_or_b32_e32 v120, 12, v112
	v_bitop3_b32 v121, v152, v120, v153 bitop3:0x36
	v_lshl_add_u32 v121, v121, 4, v154
	ds_read_b64_tr_b16 v[148:149], v121
	v_bitop3_b32 v121, v155, v120, v156 bitop3:0x36
	v_lshl_add_u32 v121, v121, 4, v157
	ds_read_b64_tr_b16 v[150:151], v121
	v_or_b32_e32 v121, 14, v112
	v_bitop3_b32 v134, v152, v121, v153 bitop3:0x36
	v_lshl_add_u32 v134, v134, 4, v154
	ds_read_b64_tr_b16 v[152:153], v134
	v_bitop3_b32 v134, v155, v121, v156 bitop3:0x36
	v_lshl_add_u32 v134, v134, 4, v157
	ds_read_b64_tr_b16 v[154:155], v134
	s_waitcnt lgkmcnt(0)
	s_add_i32 s69, s69, s67
	v_add_u32_e32 v134, s69, v115
	v_add_u32_e32 v135, s69, v113
	v_lshlrev_b32_e32 v156, 2, v134
	v_and_b32_e32 v168, 12, v156
	v_bfe_u32 v169, v134, 2, 2
	v_lshl_add_u32 v170, v134, 8, v111
	v_lshlrev_b32_e32 v134, 2, v135
	v_and_b32_e32 v171, 12, v134
	v_bitop3_b32 v134, v168, v112, v169 bitop3:0x36
	v_bfe_u32 v172, v135, 2, 2
	v_lshl_add_u32 v134, v134, 4, v170
	v_mfma_f32_16x16x32_bf16 v[122:125], v[122:125], v[100:103], 0
	v_lshl_add_u32 v173, v135, 8, v111
	v_mfma_f32_16x16x32_bf16 v[130:133], v[130:133], v[100:103], 0
	v_mfma_f32_16x16x32_bf16 v[148:151], v[148:151], v[100:103], 0
	v_mfma_f32_16x16x32_bf16 v[100:103], v[152:155], v[100:103], 0
	ds_read_b64_tr_b16 v[152:153], v134
	v_bitop3_b32 v134, v171, v112, v172 bitop3:0x36
	v_lshl_add_u32 v134, v134, 4, v173
	ds_read_b64_tr_b16 v[154:155], v134
	v_bitop3_b32 v134, v168, v114, v169 bitop3:0x36
	v_lshl_add_u32 v134, v134, 4, v170
	ds_read_b64_tr_b16 v[156:157], v134
	v_bitop3_b32 v134, v171, v114, v172 bitop3:0x36
	v_lshl_add_u32 v134, v134, 4, v173
	ds_read_b64_tr_b16 v[158:159], v134
	v_bitop3_b32 v134, v168, v116, v169 bitop3:0x36
	v_lshl_add_u32 v134, v134, 4, v170
	ds_read_b64_tr_b16 v[160:161], v134
	v_bitop3_b32 v134, v171, v116, v172 bitop3:0x36
	v_lshl_add_u32 v134, v134, 4, v173
	ds_read_b64_tr_b16 v[162:163], v134
	v_bitop3_b32 v134, v168, v117, v169 bitop3:0x36
	v_lshl_add_u32 v134, v134, 4, v170
	ds_read_b64_tr_b16 v[164:165], v134
	v_bitop3_b32 v134, v171, v117, v172 bitop3:0x36
	v_lshl_add_u32 v134, v134, 4, v173
	ds_read_b64_tr_b16 v[166:167], v134
	s_waitcnt lgkmcnt(0)
; __device__ __forceinline__ s16x4 tr_read_b64(unsigned addr) { s16x4 r; asm volatile("ds_read_b64_tr_b16 %0, %1" : "=v"(r) : "v"(addr) : "memory"); return r; }
; template <int L>
; __device__ __forceinline__ void layer_body(const Args& args, LAS unsigned char* lds, const int wave, const int G, const int gw, const int NGW, const int lo, const int hi,
;                                            unsigned char* const ws_kernel, const XcdBarrier& bar, int& pid) {
;     ...
;                     for (int s = 0; s < 8; ++s) {
;                         const int ir0 = (r0w - krlo + s) * 40 + coloff;
; #pragma unroll
;                         for (int mh = 0; mh < 2; ++mh) {
;                             s16x4 lo[4], hi[4];
; #pragma unroll
;                             for (int m4 = 0; m4 < 4; ++m4) { const int mt = mh * 4 + m4, r0_ = ir0 + 4 * kg + trq, r1_ = ir0 + 16 + 4 * kg + trq, ch_ = 2 * mt + (trp >> 1);
;                                 lo[m4] = tr_read_b64(IMG + vimg_off(r0_, ch_) + 8u * (trp & 1)); hi[m4] = tr_read_b64(IMG + vimg_off(r1_, ch_) + 8u * (trp & 1)); }
;                             asm volatile("s_waitcnt lgkmcnt(0)" ::: "memory"); __builtin_amdgcn_sched_barrier(0);
; #pragma unroll
;                             for (int m4 = 0; m4 < 4; ++m4) { const int mt = mh * 4 + m4; const bf16x8 va = (bf16x8){lo[m4][0], lo[m4][1], lo[m4][2], lo[m4][3], hi[m4][0], hi[m4][1], hi[m4][2], hi[m4][3]};
;                                 acc[mt] = __builtin_amdgcn_mfma_f32_16x16x32_bf16(va, pbf[s], acc[mt], 0, 0, 0); }
	v_bitop3_b32 v134, v168, v118, v169 bitop3:0x36
	v_lshl_add_u32 v174, v134, 4, v170
	v_mfma_f32_16x16x32_bf16 v[134:137], v[152:155], v[96:99], v[136:139]
	v_bitop3_b32 v152, v171, v118, v172 bitop3:0x36
	ds_read_b64_tr_b16 v[138:139], v174
	v_lshl_add_u32 v174, v152, 4, v173
	v_mfma_f32_16x16x32_bf16 v[152:155], v[156:159], v[96:99], v[140:143]
	ds_read_b64_tr_b16 v[140:141], v174
	v_bitop3_b32 v156, v171, v119, v172 bitop3:0x36
	v_mfma_f32_16x16x32_bf16 v[126:129], v[160:163], v[96:99], v[126:129]
	s_nop 0
	v_bitop3_b32 v142, v168, v119, v169 bitop3:0x36
	v_lshl_add_u32 v142, v142, 4, v170
	ds_read_b64_tr_b16 v[142:143], v142
	v_lshl_add_u32 v160, v156, 4, v173
	v_mfma_f32_16x16x32_bf16 v[156:159], v[164:167], v[96:99], v[144:147]
	ds_read_b64_tr_b16 v[144:145], v160
	s_nop 2
	v_bitop3_b32 v146, v168, v120, v169 bitop3:0x36
	v_lshl_add_u32 v146, v146, 4, v170
	ds_read_b64_tr_b16 v[160:161], v146
	v_bitop3_b32 v146, v171, v120, v172 bitop3:0x36
	v_lshl_add_u32 v146, v146, 4, v173
	ds_read_b64_tr_b16 v[162:163], v146
	v_bitop3_b32 v146, v168, v121, v169 bitop3:0x36
	v_lshl_add_u32 v146, v146, 4, v170
	ds_read_b64_tr_b16 v[164:165], v146
	v_bitop3_b32 v146, v171, v121, v172 bitop3:0x36
	v_lshl_add_u32 v146, v146, 4, v173
	ds_read_b64_tr_b16 v[166:167], v146
	s_waitcnt lgkmcnt(0)
	s_add_i32 s70, s70, s67
	v_add_u32_e32 v146, s70, v115
	v_mfma_f32_16x16x32_bf16 v[122:125], v[138:141], v[96:99], v[122:125]
	v_add_u32_e32 v147, s70, v113
	v_lshlrev_b32_e32 v138, 2, v146
	v_and_b32_e32 v168, 12, v138
	v_mfma_f32_16x16x32_bf16 v[130:133], v[142:145], v[96:99], v[130:133]
	v_bfe_u32 v169, v146, 2, 2
	v_lshlrev_b32_e32 v142, 2, v147
	v_lshl_add_u32 v170, v146, 8, v111
	v_mfma_f32_16x16x32_bf16 v[138:141], v[160:163], v[96:99], v[148:151]
	v_and_b32_e32 v171, 12, v142
	v_bfe_u32 v172, v147, 2, 2
	v_lshl_add_u32 v173, v147, 8, v111
	v_mfma_f32_16x16x32_bf16 v[96:99], v[164:167], v[96:99], v[100:103]
	v_bitop3_b32 v142, v168, v114, v169 bitop3:0x36
	v_lshl_add_u32 v142, v142, 4, v170
	v_bitop3_b32 v144, v171, v114, v172 bitop3:0x36
	v_bitop3_b32 v100, v168, v112, v169 bitop3:0x36
	v_lshl_add_u32 v100, v100, 4, v170
	v_bitop3_b32 v102, v171, v112, v172 bitop3:0x36
	ds_read_b64_tr_b16 v[100:101], v100
	v_lshl_add_u32 v102, v102, 4, v173
	ds_read_b64_tr_b16 v[102:103], v102
	ds_read_b64_tr_b16 v[142:143], v142
	v_lshl_add_u32 v144, v144, 4, v173
	v_bitop3_b32 v146, v168, v116, v169 bitop3:0x36
	ds_read_b64_tr_b16 v[144:145], v144
	v_lshl_add_u32 v146, v146, 4, v170
	v_bitop3_b32 v148, v171, v116, v172 bitop3:0x36
	ds_read_b64_tr_b16 v[146:147], v146
	v_lshl_add_u32 v148, v148, 4, v173
	v_bitop3_b32 v150, v168, v117, v169 bitop3:0x36
	ds_read_b64_tr_b16 v[148:149], v148
	v_lshl_add_u32 v150, v150, 4, v170
	ds_read_b64_tr_b16 v[160:161], v150
	v_bitop3_b32 v150, v171, v117, v172 bitop3:0x36
	v_lshl_add_u32 v150, v150, 4, v173
	ds_read_b64_tr_b16 v[162:163], v150
	s_waitcnt lgkmcnt(0)
	v_bitop3_b32 v150, v168, v118, v169 bitop3:0x36
	v_mfma_f32_16x16x32_bf16 v[100:103], v[100:103], v[92:95], v[134:137]
	v_lshl_add_u32 v150, v150, 4, v170
	ds_read_b64_tr_b16 v[134:135], v150
	v_bitop3_b32 v150, v168, v119, v169 bitop3:0x36
	v_mfma_f32_16x16x32_bf16 v[126:129], v[146:149], v[92:95], v[126:129]
	v_bitop3_b32 v136, v171, v118, v172 bitop3:0x36
	v_lshl_add_u32 v136, v136, 4, v173
	ds_read_b64_tr_b16 v[136:137], v136
	v_bitop3_b32 v148, v171, v119, v172 bitop3:0x36
	v_mfma_f32_16x16x32_bf16 v[142:145], v[142:145], v[92:95], v[152:155]
	v_lshl_add_u32 v150, v150, 4, v170
	ds_read_b64_tr_b16 v[146:147], v150
	v_lshl_add_u32 v148, v148, 4, v173
	v_mfma_f32_16x16x32_bf16 v[150:153], v[160:163], v[92:95], v[156:159]
	v_bitop3_b32 v154, v168, v120, v169 bitop3:0x36
	ds_read_b64_tr_b16 v[148:149], v148
	v_lshl_add_u32 v154, v154, 4, v170
	ds_read_b64_tr_b16 v[154:155], v154
	v_bitop3_b32 v160, v171, v121, v172 bitop3:0x36
	v_bitop3_b32 v156, v171, v120, v172 bitop3:0x36
	v_lshl_add_u32 v156, v156, 4, v173
	v_bitop3_b32 v158, v168, v121, v169 bitop3:0x36
	ds_read_b64_tr_b16 v[156:157], v156
	v_lshl_add_u32 v158, v158, 4, v170
	ds_read_b64_tr_b16 v[158:159], v158
	v_lshl_add_u32 v160, v160, 4, v173
	ds_read_b64_tr_b16 v[160:161], v160
	s_waitcnt lgkmcnt(0)
	s_add_i32 s71, s71, s67
	v_add_u32_e32 v162, s71, v115
	v_mfma_f32_16x16x32_bf16 v[122:125], v[134:137], v[92:95], v[122:125]
	v_add_u32_e32 v163, s71, v113
	v_lshlrev_b32_e32 v134, 2, v162
	v_and_b32_e32 v164, 12, v134
	v_mfma_f32_16x16x32_bf16 v[130:133], v[146:149], v[92:95], v[130:133]
	v_bfe_u32 v165, v162, 2, 2
	v_lshlrev_b32_e32 v146, 2, v163
	v_lshl_add_u32 v162, v162, 8, v111
	v_mfma_f32_16x16x32_bf16 v[134:137], v[154:157], v[92:95], v[138:141]
	v_and_b32_e32 v166, 12, v146
	v_bfe_u32 v167, v163, 2, 2
	v_lshl_add_u32 v163, v163, 8, v111
	v_mfma_f32_16x16x32_bf16 v[92:95], v[158:161], v[92:95], v[96:99]
	v_bitop3_b32 v138, v164, v114, v165 bitop3:0x36
	v_lshl_add_u32 v138, v138, 4, v162
	v_bitop3_b32 v140, v166, v114, v167 bitop3:0x36
	v_bitop3_b32 v96, v164, v112, v165 bitop3:0x36
	v_lshl_add_u32 v96, v96, 4, v162
	v_bitop3_b32 v98, v166, v112, v167 bitop3:0x36
	ds_read_b64_tr_b16 v[96:97], v96
	v_lshl_add_u32 v98, v98, 4, v163
	ds_read_b64_tr_b16 v[98:99], v98
	ds_read_b64_tr_b16 v[138:139], v138
	v_lshl_add_u32 v140, v140, 4, v163
	v_bitop3_b32 v146, v164, v116, v165 bitop3:0x36
	ds_read_b64_tr_b16 v[140:141], v140
	v_lshl_add_u32 v146, v146, 4, v162
	v_bitop3_b32 v148, v166, v116, v167 bitop3:0x36
	ds_read_b64_tr_b16 v[146:147], v146
	v_lshl_add_u32 v148, v148, 4, v163
	v_bitop3_b32 v154, v164, v117, v165 bitop3:0x36
	ds_read_b64_tr_b16 v[148:149], v148
	v_lshl_add_u32 v154, v154, 4, v162
	v_bitop3_b32 v156, v166, v117, v167 bitop3:0x36
	ds_read_b64_tr_b16 v[154:155], v154
	v_lshl_add_u32 v156, v156, 4, v163
	ds_read_b64_tr_b16 v[156:157], v156
	s_waitcnt lgkmcnt(0)
; __device__ __forceinline__ s16x4 tr_read_b64(unsigned addr) { s16x4 r; asm volatile("ds_read_b64_tr_b16 %0, %1" : "=v"(r) : "v"(addr) : "memory"); return r; }
; template <int L>
; __device__ __forceinline__ void layer_body(const Args& args, LAS unsigned char* lds, const int wave, const int G, const int gw, const int NGW, const int lo, const int hi,
;                                            unsigned char* const ws_kernel, const XcdBarrier& bar, int& pid) {
;     ...
;                     for (int s = 0; s < 8; ++s) {
;                         const int ir0 = (r0w - krlo + s) * 40 + coloff;
; #pragma unroll
;                         for (int mh = 0; mh < 2; ++mh) {
;                             s16x4 lo[4], hi[4];
; #pragma unroll
;                             for (int m4 = 0; m4 < 4; ++m4) { const int mt = mh * 4 + m4, r0_ = ir0 + 4 * kg + trq, r1_ = ir0 + 16 + 4 * kg + trq, ch_ = 2 * mt + (trp >> 1);
;                                 lo[m4] = tr_read_b64(IMG + vimg_off(r0_, ch_) + 8u * (trp & 1)); hi[m4] = tr_read_b64(IMG + vimg_off(r1_, ch_) + 8u * (trp & 1)); }
;                             asm volatile("s_waitcnt lgkmcnt(0)" ::: "memory"); __builtin_amdgcn_sched_barrier(0);
; #pragma unroll
;                             for (int m4 = 0; m4 < 4; ++m4) { const int mt = mh * 4 + m4; const bf16x8 va = (bf16x8){lo[m4][0], lo[m4][1], lo[m4][2], lo[m4][3], hi[m4][0], hi[m4][1], hi[m4][2], hi[m4][3]};
;                                 acc[mt] = __builtin_amdgcn_mfma_f32_16x16x32_bf16(va, pbf[s], acc[mt], 0, 0, 0); }
	v_bitop3_b32 v158, v164, v118, v165 bitop3:0x36
	v_mfma_f32_16x16x32_bf16 v[96:99], v[96:99], v[88:91], v[100:103]
	v_lshl_add_u32 v158, v158, 4, v162
	ds_read_b64_tr_b16 v[100:101], v158
	v_mfma_f32_16x16x32_bf16 v[138:141], v[138:141], v[88:91], v[142:145]
	s_nop 0
	v_bitop3_b32 v102, v166, v118, v167 bitop3:0x36
	v_lshl_add_u32 v102, v102, 4, v163
	ds_read_b64_tr_b16 v[102:103], v102
	v_mfma_f32_16x16x32_bf16 v[126:129], v[146:149], v[88:91], v[126:129]
	v_bitop3_b32 v142, v164, v119, v165 bitop3:0x36
	v_lshl_add_u32 v142, v142, 4, v162
	v_bitop3_b32 v144, v166, v119, v167 bitop3:0x36
	ds_read_b64_tr_b16 v[142:143], v142
	v_lshl_add_u32 v144, v144, 4, v163
	v_mfma_f32_16x16x32_bf16 v[146:149], v[154:157], v[88:91], v[150:153]
	ds_read_b64_tr_b16 v[144:145], v144
	v_bitop3_b32 v154, v164, v121, v165 bitop3:0x36
	v_lshl_add_u32 v154, v154, 4, v162
	v_bitop3_b32 v156, v166, v121, v167 bitop3:0x36
	v_bitop3_b32 v150, v164, v120, v165 bitop3:0x36
	v_lshl_add_u32 v150, v150, 4, v162
	v_bitop3_b32 v152, v166, v120, v167 bitop3:0x36
	ds_read_b64_tr_b16 v[150:151], v150
	v_lshl_add_u32 v152, v152, 4, v163
	ds_read_b64_tr_b16 v[152:153], v152
	ds_read_b64_tr_b16 v[154:155], v154
	v_lshl_add_u32 v156, v156, 4, v163
	ds_read_b64_tr_b16 v[156:157], v156
	s_waitcnt lgkmcnt(0)
	s_add_i32 s72, s72, s67
	v_add_u32_e32 v158, s72, v115
	v_mfma_f32_16x16x32_bf16 v[100:103], v[100:103], v[88:91], v[122:125]
	v_add_u32_e32 v159, s72, v113
	v_bfe_u32 v161, v158, 2, 2
	v_bfe_u32 v163, v159, 2, 2
	v_lshlrev_b32_e32 v122, 2, v158
	v_and_b32_e32 v160, 12, v122
	v_mfma_f32_16x16x32_bf16 v[122:125], v[142:145], v[88:91], v[130:133]
	v_lshlrev_b32_e32 v142, 2, v159
	v_lshl_add_u32 v158, v158, 8, v111
	v_and_b32_e32 v162, 12, v142
	v_mfma_f32_16x16x32_bf16 v[130:133], v[150:153], v[88:91], v[134:137]
	v_lshl_add_u32 v159, v159, 8, v111
	v_bitop3_b32 v142, v160, v116, v161 bitop3:0x36
	v_lshl_add_u32 v142, v142, 4, v158
	v_mfma_f32_16x16x32_bf16 v[88:91], v[154:157], v[88:91], v[92:95]
	v_bitop3_b32 v134, v160, v114, v161 bitop3:0x36
	v_lshl_add_u32 v134, v134, 4, v158
	v_bitop3_b32 v136, v162, v114, v163 bitop3:0x36
	v_bitop3_b32 v92, v160, v112, v161 bitop3:0x36
	v_lshl_add_u32 v92, v92, 4, v158
	v_bitop3_b32 v94, v162, v112, v163 bitop3:0x36
	ds_read_b64_tr_b16 v[92:93], v92
	v_lshl_add_u32 v94, v94, 4, v159
	ds_read_b64_tr_b16 v[94:95], v94
	ds_read_b64_tr_b16 v[134:135], v134
	v_lshl_add_u32 v136, v136, 4, v159
	ds_read_b64_tr_b16 v[136:137], v136
	v_bitop3_b32 v144, v162, v116, v163 bitop3:0x36
	ds_read_b64_tr_b16 v[142:143], v142
	v_lshl_add_u32 v144, v144, 4, v159
	v_bitop3_b32 v150, v160, v117, v161 bitop3:0x36
	ds_read_b64_tr_b16 v[144:145], v144
	v_lshl_add_u32 v150, v150, 4, v158
	v_bitop3_b32 v152, v162, v117, v163 bitop3:0x36
	ds_read_b64_tr_b16 v[150:151], v150
	v_lshl_add_u32 v152, v152, 4, v159
	ds_read_b64_tr_b16 v[152:153], v152
	s_waitcnt lgkmcnt(0)
	v_bitop3_b32 v154, v160, v118, v161 bitop3:0x36
	v_mfma_f32_16x16x32_bf16 v[92:95], v[92:95], v[84:87], v[96:99]
	v_lshl_add_u32 v154, v154, 4, v158
	ds_read_b64_tr_b16 v[96:97], v154
	v_mfma_f32_16x16x32_bf16 v[134:137], v[134:137], v[84:87], v[138:141]
	s_nop 0
	v_bitop3_b32 v98, v162, v118, v163 bitop3:0x36
	v_lshl_add_u32 v98, v98, 4, v159
	ds_read_b64_tr_b16 v[98:99], v98
	v_mfma_f32_16x16x32_bf16 v[126:129], v[142:145], v[84:87], v[126:129]
	v_bitop3_b32 v138, v160, v119, v161 bitop3:0x36
	v_lshl_add_u32 v138, v138, 4, v158
	v_bitop3_b32 v140, v162, v119, v163 bitop3:0x36
	ds_read_b64_tr_b16 v[138:139], v138
	v_lshl_add_u32 v140, v140, 4, v159
	v_mfma_f32_16x16x32_bf16 v[142:145], v[150:153], v[84:87], v[146:149]
	ds_read_b64_tr_b16 v[140:141], v140
	v_bitop3_b32 v150, v160, v121, v161 bitop3:0x36
	v_lshl_add_u32 v150, v150, 4, v158
	v_bitop3_b32 v152, v162, v121, v163 bitop3:0x36
	v_bitop3_b32 v146, v160, v120, v161 bitop3:0x36
	v_lshl_add_u32 v146, v146, 4, v158
	v_bitop3_b32 v148, v162, v120, v163 bitop3:0x36
	ds_read_b64_tr_b16 v[146:147], v146
	v_lshl_add_u32 v148, v148, 4, v159
	ds_read_b64_tr_b16 v[148:149], v148
	ds_read_b64_tr_b16 v[150:151], v150
	v_lshl_add_u32 v152, v152, 4, v159
	ds_read_b64_tr_b16 v[152:153], v152
	s_waitcnt lgkmcnt(0)
	s_add_i32 s74, s74, s67
	v_add_u32_e32 v154, s74, v115
	v_mfma_f32_16x16x32_bf16 v[96:99], v[96:99], v[84:87], v[100:103]
	v_add_u32_e32 v155, s74, v113
	v_bfe_u32 v157, v154, 2, 2
	v_bfe_u32 v159, v155, 2, 2
	v_lshlrev_b32_e32 v100, 2, v154
	v_and_b32_e32 v156, 12, v100
	v_mfma_f32_16x16x32_bf16 v[100:103], v[138:141], v[84:87], v[122:125]
	v_lshlrev_b32_e32 v138, 2, v155
	v_lshl_add_u32 v154, v154, 8, v111
	v_and_b32_e32 v158, 12, v138
	v_mfma_f32_16x16x32_bf16 v[122:125], v[146:149], v[84:87], v[130:133]
	v_lshl_add_u32 v155, v155, 8, v111
	v_bitop3_b32 v138, v156, v116, v157 bitop3:0x36
	v_lshl_add_u32 v138, v138, 4, v154
	v_mfma_f32_16x16x32_bf16 v[84:87], v[150:153], v[84:87], v[88:91]
	v_bitop3_b32 v130, v156, v114, v157 bitop3:0x36
	v_lshl_add_u32 v130, v130, 4, v154
	v_bitop3_b32 v132, v158, v114, v159 bitop3:0x36
	v_bitop3_b32 v88, v156, v112, v157 bitop3:0x36
	v_lshl_add_u32 v88, v88, 4, v154
	v_bitop3_b32 v90, v158, v112, v159 bitop3:0x36
	ds_read_b64_tr_b16 v[88:89], v88
	v_lshl_add_u32 v90, v90, 4, v155
	ds_read_b64_tr_b16 v[90:91], v90
	ds_read_b64_tr_b16 v[130:131], v130
	v_lshl_add_u32 v132, v132, 4, v155
	ds_read_b64_tr_b16 v[132:133], v132
	v_bitop3_b32 v140, v158, v116, v159 bitop3:0x36
	ds_read_b64_tr_b16 v[138:139], v138
	v_lshl_add_u32 v140, v140, 4, v155
	v_bitop3_b32 v146, v156, v117, v157 bitop3:0x36
	ds_read_b64_tr_b16 v[140:141], v140
	v_lshl_add_u32 v146, v146, 4, v154
	v_bitop3_b32 v148, v158, v117, v159 bitop3:0x36
	ds_read_b64_tr_b16 v[146:147], v146
	v_lshl_add_u32 v148, v148, 4, v155
	ds_read_b64_tr_b16 v[148:149], v148
	s_waitcnt lgkmcnt(0)
; __device__ __forceinline__ s16x4 tr_read_b64(unsigned addr) { s16x4 r; asm volatile("ds_read_b64_tr_b16 %0, %1" : "=v"(r) : "v"(addr) : "memory"); return r; }
; template <int L>
; __device__ __forceinline__ void layer_body(const Args& args, LAS unsigned char* lds, const int wave, const int G, const int gw, const int NGW, const int lo, const int hi,
;                                            unsigned char* const ws_kernel, const XcdBarrier& bar, int& pid) {
;     ...
;                     for (int s = 0; s < 8; ++s) {
;                         const int ir0 = (r0w - krlo + s) * 40 + coloff;
; #pragma unroll
;                         for (int mh = 0; mh < 2; ++mh) {
;                             s16x4 lo[4], hi[4];
; #pragma unroll
;                             for (int m4 = 0; m4 < 4; ++m4) { const int mt = mh * 4 + m4, r0_ = ir0 + 4 * kg + trq, r1_ = ir0 + 16 + 4 * kg + trq, ch_ = 2 * mt + (trp >> 1);
;                                 lo[m4] = tr_read_b64(IMG + vimg_off(r0_, ch_) + 8u * (trp & 1)); hi[m4] = tr_read_b64(IMG + vimg_off(r1_, ch_) + 8u * (trp & 1)); }
;                             asm volatile("s_waitcnt lgkmcnt(0)" ::: "memory"); __builtin_amdgcn_sched_barrier(0);
; #pragma unroll
;                             for (int m4 = 0; m4 < 4; ++m4) { const int mt = mh * 4 + m4; const bf16x8 va = (bf16x8){lo[m4][0], lo[m4][1], lo[m4][2], lo[m4][3], hi[m4][0], hi[m4][1], hi[m4][2], hi[m4][3]};
;                                 acc[mt] = __builtin_amdgcn_mfma_f32_16x16x32_bf16(va, pbf[s], acc[mt], 0, 0, 0); }
	v_bitop3_b32 v150, v156, v118, v157 bitop3:0x36
	v_mfma_f32_16x16x32_bf16 v[88:91], v[88:91], v[80:83], v[92:95]
	v_lshl_add_u32 v150, v150, 4, v154
	ds_read_b64_tr_b16 v[92:93], v150
	v_mfma_f32_16x16x32_bf16 v[130:133], v[130:133], v[80:83], v[134:137]
	s_nop 0
	v_bitop3_b32 v94, v158, v118, v159 bitop3:0x36
	v_lshl_add_u32 v94, v94, 4, v155
	ds_read_b64_tr_b16 v[94:95], v94
	v_mfma_f32_16x16x32_bf16 v[126:129], v[138:141], v[80:83], v[126:129]
	v_bitop3_b32 v134, v156, v119, v157 bitop3:0x36
	v_lshl_add_u32 v134, v134, 4, v154
	v_bitop3_b32 v136, v158, v119, v159 bitop3:0x36
	ds_read_b64_tr_b16 v[134:135], v134
	v_lshl_add_u32 v136, v136, 4, v155
	v_mfma_f32_16x16x32_bf16 v[138:141], v[146:149], v[80:83], v[142:145]
	ds_read_b64_tr_b16 v[136:137], v136
	v_bitop3_b32 v146, v156, v121, v157 bitop3:0x36
	v_lshl_add_u32 v146, v146, 4, v154
	v_bitop3_b32 v148, v158, v121, v159 bitop3:0x36
	v_bitop3_b32 v142, v156, v120, v157 bitop3:0x36
	v_lshl_add_u32 v142, v142, 4, v154
	v_bitop3_b32 v144, v158, v120, v159 bitop3:0x36
	ds_read_b64_tr_b16 v[142:143], v142
	v_lshl_add_u32 v144, v144, 4, v155
	ds_read_b64_tr_b16 v[144:145], v144
	ds_read_b64_tr_b16 v[146:147], v146
	v_lshl_add_u32 v148, v148, 4, v155
	ds_read_b64_tr_b16 v[148:149], v148
	s_waitcnt lgkmcnt(0)
	s_add_i32 s75, s75, s67
	v_add_u32_e32 v150, s75, v115
	v_mfma_f32_16x16x32_bf16 v[92:95], v[92:95], v[80:83], v[96:99]
	v_add_u32_e32 v151, s75, v113
	v_bfe_u32 v153, v150, 2, 2
	v_bfe_u32 v155, v151, 2, 2
	v_lshlrev_b32_e32 v96, 2, v150
	v_and_b32_e32 v152, 12, v96
	v_mfma_f32_16x16x32_bf16 v[96:99], v[134:137], v[80:83], v[100:103]
	v_lshlrev_b32_e32 v134, 2, v151
	v_lshl_add_u32 v150, v150, 8, v111
	v_and_b32_e32 v154, 12, v134
	v_mfma_f32_16x16x32_bf16 v[100:103], v[142:145], v[80:83], v[122:125]
	v_lshl_add_u32 v151, v151, 8, v111
	v_bitop3_b32 v134, v152, v116, v153 bitop3:0x36
	v_lshl_add_u32 v134, v134, 4, v150
	v_mfma_f32_16x16x32_bf16 v[80:83], v[146:149], v[80:83], v[84:87]
	v_bitop3_b32 v122, v152, v114, v153 bitop3:0x36
	v_lshl_add_u32 v122, v122, 4, v150
	v_bitop3_b32 v124, v154, v114, v155 bitop3:0x36
	v_bitop3_b32 v84, v152, v112, v153 bitop3:0x36
	v_lshl_add_u32 v84, v84, 4, v150
	v_bitop3_b32 v86, v154, v112, v155 bitop3:0x36
	ds_read_b64_tr_b16 v[84:85], v84
	v_lshl_add_u32 v86, v86, 4, v151
	ds_read_b64_tr_b16 v[86:87], v86
	ds_read_b64_tr_b16 v[122:123], v122
	v_lshl_add_u32 v124, v124, 4, v151
	ds_read_b64_tr_b16 v[124:125], v124
	v_bitop3_b32 v136, v154, v116, v155 bitop3:0x36
	ds_read_b64_tr_b16 v[134:135], v134
	v_lshl_add_u32 v136, v136, 4, v151
	v_bitop3_b32 v142, v152, v117, v153 bitop3:0x36
	ds_read_b64_tr_b16 v[136:137], v136
	v_lshl_add_u32 v142, v142, 4, v150
	v_bitop3_b32 v144, v154, v117, v155 bitop3:0x36
	ds_read_b64_tr_b16 v[142:143], v142
	v_lshl_add_u32 v144, v144, 4, v151
	ds_read_b64_tr_b16 v[144:145], v144
	s_waitcnt lgkmcnt(0)
	v_bitop3_b32 v146, v152, v118, v153 bitop3:0x36
	v_mfma_f32_16x16x32_bf16 v[84:87], v[84:87], v[76:79], v[88:91]
	v_lshl_add_u32 v146, v146, 4, v150
	ds_read_b64_tr_b16 v[88:89], v146
	v_mfma_f32_16x16x32_bf16 v[122:125], v[122:125], v[76:79], v[130:133]
	s_nop 0
	v_bitop3_b32 v90, v154, v118, v155 bitop3:0x36
	v_lshl_add_u32 v90, v90, 4, v151
	ds_read_b64_tr_b16 v[90:91], v90
	v_mfma_f32_16x16x32_bf16 v[126:129], v[134:137], v[76:79], v[126:129]
	v_bitop3_b32 v130, v152, v119, v153 bitop3:0x36
	v_lshl_add_u32 v130, v130, 4, v150
	v_bitop3_b32 v132, v154, v119, v155 bitop3:0x36
	ds_read_b64_tr_b16 v[130:131], v130
	v_lshl_add_u32 v132, v132, 4, v151
	v_mfma_f32_16x16x32_bf16 v[134:137], v[142:145], v[76:79], v[138:141]
	ds_read_b64_tr_b16 v[132:133], v132
	v_bitop3_b32 v142, v152, v121, v153 bitop3:0x36
	v_lshl_add_u32 v142, v142, 4, v150
	v_bitop3_b32 v144, v154, v121, v155 bitop3:0x36
	v_bitop3_b32 v138, v152, v120, v153 bitop3:0x36
	v_lshl_add_u32 v138, v138, 4, v150
	v_bitop3_b32 v140, v154, v120, v155 bitop3:0x36
	ds_read_b64_tr_b16 v[138:139], v138
	v_lshl_add_u32 v140, v140, 4, v151
	ds_read_b64_tr_b16 v[140:141], v140
	ds_read_b64_tr_b16 v[142:143], v142
	v_lshl_add_u32 v144, v144, 4, v151
	ds_read_b64_tr_b16 v[144:145], v144
	s_waitcnt lgkmcnt(0)
	s_add_i32 s76, s76, s67
	v_add_u32_e32 v115, s76, v115
	v_mfma_f32_16x16x32_bf16 v[88:91], v[88:91], v[76:79], v[92:95]
	v_add_u32_e32 v113, s76, v113
	v_bfe_u32 v147, v115, 2, 2
	v_lshl_add_u32 v148, v115, 8, v111
	v_lshlrev_b32_e32 v92, 2, v115
	v_and_b32_e32 v146, 12, v92
	v_lshlrev_b32_e32 v115, 2, v113
	v_mfma_f32_16x16x32_bf16 v[92:95], v[130:133], v[76:79], v[96:99]
	v_lshl_add_u32 v111, v113, 8, v111
	v_mfma_f32_16x16x32_bf16 v[96:99], v[138:141], v[76:79], v[100:103]
	v_and_b32_e32 v138, 12, v115
	v_bfe_u32 v139, v113, 2, 2
	v_mfma_f32_16x16x32_bf16 v[76:79], v[142:145], v[76:79], v[80:83]
	v_bitop3_b32 v100, v146, v114, v147 bitop3:0x36
	v_lshl_add_u32 v100, v100, 4, v148
	v_bitop3_b32 v102, v138, v114, v139 bitop3:0x36
	v_bitop3_b32 v80, v146, v112, v147 bitop3:0x36
	v_lshl_add_u32 v80, v80, 4, v148
	v_bitop3_b32 v82, v138, v112, v139 bitop3:0x36
	ds_read_b64_tr_b16 v[80:81], v80
	v_lshl_add_u32 v82, v82, 4, v111
	ds_read_b64_tr_b16 v[82:83], v82
	ds_read_b64_tr_b16 v[100:101], v100
	v_lshl_add_u32 v102, v102, 4, v111
	v_bitop3_b32 v112, v146, v116, v147 bitop3:0x36
	ds_read_b64_tr_b16 v[102:103], v102
	v_lshl_add_u32 v112, v112, 4, v148
	v_bitop3_b32 v114, v138, v116, v139 bitop3:0x36
	ds_read_b64_tr_b16 v[112:113], v112
	v_lshl_add_u32 v114, v114, 4, v111
	v_bitop3_b32 v116, v146, v117, v147 bitop3:0x36
	ds_read_b64_tr_b16 v[114:115], v114
	v_lshl_add_u32 v116, v116, 4, v148
	ds_read_b64_tr_b16 v[130:131], v116
	v_bitop3_b32 v116, v138, v117, v139 bitop3:0x36
	v_lshl_add_u32 v116, v116, 4, v111
	ds_read_b64_tr_b16 v[132:133], v116
	s_waitcnt lgkmcnt(0)
; __device__ __forceinline__ s16x4 tr_read_b64(unsigned addr) { s16x4 r; asm volatile("ds_read_b64_tr_b16 %0, %1" : "=v"(r) : "v"(addr) : "memory"); return r; }
; template <int L>
; __device__ __forceinline__ void layer_body(const Args& args, LAS unsigned char* lds, const int wave, const int G, const int gw, const int NGW, const int lo, const int hi,
;                                            unsigned char* const ws_kernel, const XcdBarrier& bar, int& pid) {
;     ...
;                     for (int s = 0; s < 8; ++s) {
;                         const int ir0 = (r0w - krlo + s) * 40 + coloff;
; #pragma unroll
;                         for (int mh = 0; mh < 2; ++mh) {
;                             s16x4 lo[4], hi[4];
; #pragma unroll
;                             for (int m4 = 0; m4 < 4; ++m4) { const int mt = mh * 4 + m4, r0_ = ir0 + 4 * kg + trq, r1_ = ir0 + 16 + 4 * kg + trq, ch_ = 2 * mt + (trp >> 1);
;                                 lo[m4] = tr_read_b64(IMG + vimg_off(r0_, ch_) + 8u * (trp & 1)); hi[m4] = tr_read_b64(IMG + vimg_off(r1_, ch_) + 8u * (trp & 1)); }
;                             asm volatile("s_waitcnt lgkmcnt(0)" ::: "memory"); __builtin_amdgcn_sched_barrier(0);
; #pragma unroll
;                             for (int m4 = 0; m4 < 4; ++m4) { const int mt = mh * 4 + m4; const bf16x8 va = (bf16x8){lo[m4][0], lo[m4][1], lo[m4][2], lo[m4][3], hi[m4][0], hi[m4][1], hi[m4][2], hi[m4][3]};
;                                 acc[mt] = __builtin_amdgcn_mfma_f32_16x16x32_bf16(va, pbf[s], acc[mt], 0, 0, 0); }
	v_bitop3_b32 v116, v146, v118, v147 bitop3:0x36
	v_lshl_add_u32 v116, v116, 4, v148
	v_mfma_f32_16x16x32_bf16 v[80:83], v[80:83], v[72:75], v[84:87]
	ds_read_b64_tr_b16 v[84:85], v116
	v_bitop3_b32 v116, v146, v119, v147 bitop3:0x36
	v_lshl_add_u32 v116, v116, 4, v148
	v_mfma_f32_16x16x32_bf16 v[112:115], v[112:115], v[72:75], v[126:129]
	v_bitop3_b32 v86, v138, v118, v139 bitop3:0x36
	v_lshl_add_u32 v86, v86, 4, v111
	ds_read_b64_tr_b16 v[86:87], v86
	v_bitop3_b32 v118, v138, v119, v139 bitop3:0x36
	ds_read_b64_tr_b16 v[116:117], v116
	v_lshl_add_u32 v118, v118, 4, v111
	v_bitop3_b32 v126, v146, v120, v147 bitop3:0x36
	ds_read_b64_tr_b16 v[118:119], v118
	v_lshl_add_u32 v126, v126, 4, v148
	v_bitop3_b32 v120, v138, v120, v139 bitop3:0x36
	ds_read_b64_tr_b16 v[126:127], v126
	v_lshl_add_u32 v120, v120, 4, v111
	ds_read_b64_tr_b16 v[128:129], v120
	v_bitop3_b32 v120, v146, v121, v147 bitop3:0x36
	v_lshl_add_u32 v120, v120, 4, v148
	v_mfma_f32_16x16x32_bf16 v[100:103], v[100:103], v[72:75], v[122:125]
	v_mfma_f32_16x16x32_bf16 v[122:125], v[130:133], v[72:75], v[134:137]
	ds_read_b64_tr_b16 v[130:131], v120
	v_bitop3_b32 v120, v138, v121, v139 bitop3:0x36
	v_lshl_add_u32 v111, v120, 4, v111
	ds_read_b64_tr_b16 v[132:133], v111
	s_waitcnt lgkmcnt(0)
; #define GAS __attribute__((address_space(1)))
; __device__ __forceinline__ unsigned pk2(float lo, float hi) { return f2bf(lo) | (f2bf(hi) << 16); }
; template <int L>
; __device__ __forceinline__ void layer_body(const Args& args, LAS unsigned char* lds, const int wave, const int G, const int gw, const int NGW, const int lo, const int hi,
;                                            unsigned char* const ws_kernel, const XcdBarrier& bar, int& pid) {
;     ...
;                             for (int m4 = 0; m4 < 4; ++m4) { const int mt = mh * 4 + m4; const bf16x8 va = (bf16x8){lo[m4][0], lo[m4][1], lo[m4][2], lo[m4][3], hi[m4][0], hi[m4][1], hi[m4][2], hi[m4][3]};
;                                 acc[mt] = __builtin_amdgcn_mfma_f32_16x16x32_bf16(va, pbf[s], acc[mt], 0, 0, 0); }
;                         }
;                     }
;                     const float inv = 1.0f / sum;
;                     GAS bf16* op = (GAS bf16*)(obuf + (size_t)(b * SEQ + r * 64 + c) * D + h * HD + 4 * kg);
; #pragma unroll
;                     for (int mt = 0; mt < 8; ++mt) { v2u w; w.x = pk2(acc[mt][0] * inv, acc[mt][1] * inv); w.y = pk2(acc[mt][2] * inv, acc[mt][3] * inv); *(GAS v2u*)(op + 16 * mt) = w; }
	v_div_scale_f32 v111, s[16:17], v104, v104, 1.0
	v_rcp_f32_e32 v120, v111
	v_mfma_f32_16x16x32_bf16 v[84:87], v[84:87], v[72:75], v[88:91]
	s_lshl_b32 s15, s66, 6
	s_add_i32 s15, s15, s8
	s_lshl_b32 s8, s14, 1
	v_fma_f32 v88, -v111, v120, 1.0
	v_fmac_f32_e32 v120, v88, v120
	v_mfma_f32_16x16x32_bf16 v[88:91], v[116:119], v[72:75], v[92:95]
	v_div_scale_f32 v116, vcc, 1.0, v104, 1.0
	v_mul_f32_e32 v117, v116, v120
	v_mfma_f32_16x16x32_bf16 v[92:95], v[126:129], v[72:75], v[96:99]
	s_add_i32 s53, s53, s51
	s_add_i32 s57, s57, s55
	s_nop 0
	v_fma_f32 v96, -v111, v117, v116
	v_fmac_f32_e32 v117, v96, v120
	v_fma_f32 v96, -v111, v117, v116
	v_mfma_f32_16x16x32_bf16 v[72:75], v[130:133], v[72:75], v[76:79]
	v_mov_b32_e32 v97, v82
	v_mov_b32_e32 v82, v81
	s_nop 0
	v_div_fmas_f32 v76, v96, v120, v117
	v_div_fixup_f32 v76, v76, v104, 1.0
	v_mov_b32_e32 v96, v80
	v_or_b32_e32 v78, s15, v110
	v_pk_mul_f32 v[96:97], v[76:77], v[96:97] op_sel_hi:[0,1]
	v_ashrrev_i32_e32 v79, 31, v78
	v_pk_mul_f32 v[80:81], v[76:77], v[82:83] op_sel_hi:[0,1]
	v_lshlrev_b64 v[78:79], 12, v[78:79]
	v_and_b32_sdwa v83, v81, v108 dst_sel:DWORD dst_unused:UNUSED_PAD src0_sel:WORD_1 src1_sel:DWORD
	v_lshl_add_u64 v[78:79], s[6:7], 0, v[78:79]
	v_and_b32_sdwa v77, v97, v108 dst_sel:DWORD dst_unused:UNUSED_PAD src0_sel:WORD_1 src1_sel:DWORD
	v_add3_u32 v81, v81, v83, s64
	v_lshl_add_u64 v[78:79], v[78:79], 0, s[8:9]
	v_lshlrev_b32_e32 v104, 1, v109
	v_add3_u32 v77, v97, v77, s64
	v_and_b32_e32 v81, 0xffff0000, v81
	v_lshl_add_u64 v[78:79], v[78:79], 0, v[104:105]
	v_or_b32_sdwa v81, v81, v77 dst_sel:DWORD dst_unused:UNUSED_PAD src0_sel:DWORD src1_sel:WORD_1
	v_cvt_pk_bf16_f32 v80, v96, v80
	global_store_dwordx2 v[78:79], v[80:81], off
	v_mov_b32_e32 v80, v100
	v_mov_b32_e32 v81, v102
	v_pk_mul_f32 v[80:81], v[76:77], v[80:81] op_sel_hi:[0,1]
	v_mov_b32_e32 v102, v101
	v_pk_mul_f32 v[82:83], v[76:77], v[102:103] op_sel_hi:[0,1]
	v_and_b32_sdwa v77, v81, v108 dst_sel:DWORD dst_unused:UNUSED_PAD src0_sel:WORD_1 src1_sel:DWORD
	v_add3_u32 v77, v81, v77, s64
	v_and_b32_sdwa v81, v83, v108 dst_sel:DWORD dst_unused:UNUSED_PAD src0_sel:WORD_1 src1_sel:DWORD
	v_add3_u32 v81, v83, v81, s64
	v_and_b32_e32 v81, 0xffff0000, v81
	v_or_b32_sdwa v81, v81, v77 dst_sel:DWORD dst_unused:UNUSED_PAD src0_sel:DWORD src1_sel:WORD_1
	v_cvt_pk_bf16_f32 v80, v80, v82
	global_store_dwordx2 v[78:79], v[80:81], off offset:32
	v_mov_b32_e32 v80, v112
	v_mov_b32_e32 v81, v114
	v_pk_mul_f32 v[80:81], v[76:77], v[80:81] op_sel_hi:[0,1]
	v_mov_b32_e32 v114, v113
	v_pk_mul_f32 v[82:83], v[76:77], v[114:115] op_sel_hi:[0,1]
	v_and_b32_sdwa v77, v81, v108 dst_sel:DWORD dst_unused:UNUSED_PAD src0_sel:WORD_1 src1_sel:DWORD
	v_add3_u32 v77, v81, v77, s64
	v_and_b32_sdwa v81, v83, v108 dst_sel:DWORD dst_unused:UNUSED_PAD src0_sel:WORD_1 src1_sel:DWORD
	v_add3_u32 v81, v83, v81, s64
	v_and_b32_e32 v81, 0xffff0000, v81
	v_or_b32_sdwa v81, v81, v77 dst_sel:DWORD dst_unused:UNUSED_PAD src0_sel:DWORD src1_sel:WORD_1
	v_cvt_pk_bf16_f32 v80, v80, v82
	global_store_dwordx2 v[78:79], v[80:81], off offset:64
	v_mov_b32_e32 v80, v122
	v_mov_b32_e32 v81, v124
	v_pk_mul_f32 v[80:81], v[76:77], v[80:81] op_sel_hi:[0,1]
	v_mov_b32_e32 v124, v123
	v_pk_mul_f32 v[82:83], v[76:77], v[124:125] op_sel_hi:[0,1]
	v_and_b32_sdwa v77, v81, v108 dst_sel:DWORD dst_unused:UNUSED_PAD src0_sel:WORD_1 src1_sel:DWORD
	v_add3_u32 v77, v81, v77, s64
	v_and_b32_sdwa v81, v83, v108 dst_sel:DWORD dst_unused:UNUSED_PAD src0_sel:WORD_1 src1_sel:DWORD
	v_add3_u32 v81, v83, v81, s64
	v_and_b32_e32 v81, 0xffff0000, v81
	v_or_b32_sdwa v81, v81, v77 dst_sel:DWORD dst_unused:UNUSED_PAD src0_sel:DWORD src1_sel:WORD_1
	v_cvt_pk_bf16_f32 v80, v80, v82
	global_store_dwordx2 v[78:79], v[80:81], off offset:96
	v_mov_b32_e32 v80, v84
	v_mov_b32_e32 v81, v86
	v_pk_mul_f32 v[80:81], v[76:77], v[80:81] op_sel_hi:[0,1]
	v_mov_b32_e32 v86, v85
	v_pk_mul_f32 v[82:83], v[76:77], v[86:87] op_sel_hi:[0,1]
	v_and_b32_sdwa v77, v81, v108 dst_sel:DWORD dst_unused:UNUSED_PAD src0_sel:WORD_1 src1_sel:DWORD
	v_add3_u32 v77, v81, v77, s64
	v_and_b32_sdwa v81, v83, v108 dst_sel:DWORD dst_unused:UNUSED_PAD src0_sel:WORD_1 src1_sel:DWORD
	v_add3_u32 v81, v83, v81, s64
	v_and_b32_e32 v81, 0xffff0000, v81
	v_or_b32_sdwa v81, v81, v77 dst_sel:DWORD dst_unused:UNUSED_PAD src0_sel:DWORD src1_sel:WORD_1
	v_cvt_pk_bf16_f32 v80, v80, v82
	global_store_dwordx2 v[78:79], v[80:81], off offset:128
	v_mov_b32_e32 v80, v88
	v_mov_b32_e32 v81, v90
	v_pk_mul_f32 v[80:81], v[76:77], v[80:81] op_sel_hi:[0,1]
	v_mov_b32_e32 v90, v89
	v_pk_mul_f32 v[82:83], v[76:77], v[90:91] op_sel_hi:[0,1]
	v_and_b32_sdwa v77, v81, v108 dst_sel:DWORD dst_unused:UNUSED_PAD src0_sel:WORD_1 src1_sel:DWORD
	v_add3_u32 v77, v81, v77, s64
	v_and_b32_sdwa v81, v83, v108 dst_sel:DWORD dst_unused:UNUSED_PAD src0_sel:WORD_1 src1_sel:DWORD
	v_add3_u32 v81, v83, v81, s64
	v_and_b32_e32 v81, 0xffff0000, v81
	v_or_b32_sdwa v81, v81, v77 dst_sel:DWORD dst_unused:UNUSED_PAD src0_sel:DWORD src1_sel:WORD_1
	v_cvt_pk_bf16_f32 v80, v80, v82
	global_store_dwordx2 v[78:79], v[80:81], off offset:160
	v_mov_b32_e32 v80, v92
	v_mov_b32_e32 v81, v94
	v_pk_mul_f32 v[80:81], v[76:77], v[80:81] op_sel_hi:[0,1]
	v_mov_b32_e32 v94, v93
	v_pk_mul_f32 v[82:83], v[76:77], v[94:95] op_sel_hi:[0,1]
	v_and_b32_sdwa v77, v81, v108 dst_sel:DWORD dst_unused:UNUSED_PAD src0_sel:WORD_1 src1_sel:DWORD
	v_add3_u32 v77, v81, v77, s64
	v_and_b32_sdwa v81, v83, v108 dst_sel:DWORD dst_unused:UNUSED_PAD src0_sel:WORD_1 src1_sel:DWORD
	v_add3_u32 v81, v83, v81, s64
	v_and_b32_e32 v81, 0xffff0000, v81
	v_or_b32_sdwa v81, v81, v77 dst_sel:DWORD dst_unused:UNUSED_PAD src0_sel:DWORD src1_sel:WORD_1
	v_cvt_pk_bf16_f32 v80, v80, v82
	global_store_dwordx2 v[78:79], v[80:81], off offset:192
	v_mov_b32_e32 v81, v74
	v_mov_b32_e32 v74, v73
	v_mov_b32_e32 v80, v72
	v_pk_mul_f32 v[72:73], v[76:77], v[74:75] op_sel_hi:[0,1]
	v_pk_mul_f32 v[80:81], v[76:77], v[80:81] op_sel_hi:[0,1]
	v_cvt_pk_bf16_f32 v73, v81, v73
	v_cvt_pk_bf16_f32 v72, v80, v72
	s_andn2_b64 vcc, exec, s[0:1]
	global_store_dwordx2 v[78:79], v[72:73], off offset:224
	s_barrier
	s_cbranch_vccz .LBB0_3541
